# decode attention compute loop: LDS fragment reads streamed up to 12 ahead with counted waits, first P.V reads issued before the softmax, max3 row max
# speedup vs baseline: 1.0128x; 1.0068x over previous
.LBB0_836:
	v_add_u32_e32 v16, s82, v182
	ds_read_b128 v[4:7], v16 offset:0
	ds_read_b128 v[194:197], v182 offset:0
	ds_read_b128 v[198:201], v182 offset:18944
	ds_read_b128 v[8:11], v16 offset:32
	ds_read_b128 v[202:205], v182 offset:32
	ds_read_b128 v[206:209], v182 offset:18976
	ds_read_b128 v[12:15], v16 offset:64
	ds_read_b128 v[210:213], v182 offset:64
	ds_read_b128 v[214:217], v182 offset:19008
	s_waitcnt lgkmcnt(7)
	v_mfma_f32_32x32x16_bf16 v[162:177], v[194:197], v[4:7], 0
	ds_read_b128 v[186:189], v16 offset:96
	ds_read_b128 v[234:237], v182 offset:96
	ds_read_b128 v[238:241], v182 offset:19040
	ds_read_b128 v[190:193], v16 offset:128
	ds_read_b128 v[242:245], v182 offset:128
	s_waitcnt lgkmcnt(11)
	v_mfma_f32_32x32x16_bf16 v[146:161], v[198:201], v[4:7], 0
	ds_read_b128 v[246:249], v182 offset:19072
	s_waitcnt lgkmcnt(10)
	v_mfma_f32_32x32x16_bf16 v[162:177], v[202:205], v[8:11], v[162:177]
	ds_read_b128 v[4:7], v16 offset:160
	ds_read_b128 v[194:197], v182 offset:160
	s_waitcnt lgkmcnt(11)
	v_mfma_f32_32x32x16_bf16 v[146:161], v[206:209], v[8:11], v[146:161]
	ds_read_b128 v[198:201], v182 offset:19104
	s_waitcnt lgkmcnt(10)
	v_mfma_f32_32x32x16_bf16 v[162:177], v[210:213], v[12:15], v[162:177]
	ds_read_b128 v[8:11], v16 offset:192
	ds_read_b128 v[202:205], v182 offset:192
	s_waitcnt lgkmcnt(11)
	v_mfma_f32_32x32x16_bf16 v[146:161], v[214:217], v[12:15], v[146:161]
	ds_read_b128 v[206:209], v182 offset:19136
	s_waitcnt lgkmcnt(10)
	v_mfma_f32_32x32x16_bf16 v[162:177], v[234:237], v[186:189], v[162:177]
	ds_read_b128 v[12:15], v16 offset:224
	ds_read_b128 v[210:213], v182 offset:224
	s_waitcnt lgkmcnt(11)
	v_mfma_f32_32x32x16_bf16 v[146:161], v[238:241], v[186:189], v[146:161]
	ds_read_b128 v[214:217], v182 offset:19168
	s_waitcnt lgkmcnt(10)
	v_mfma_f32_32x32x16_bf16 v[162:177], v[242:245], v[190:193], v[162:177]
	ds_read_b128 v[186:189], v16 offset:256
	ds_read_b128 v[234:237], v182 offset:256
	s_waitcnt lgkmcnt(11)
	v_mfma_f32_32x32x16_bf16 v[146:161], v[246:249], v[190:193], v[146:161]
	ds_read_b128 v[238:241], v182 offset:19200
	s_waitcnt lgkmcnt(10)
	v_mfma_f32_32x32x16_bf16 v[162:177], v[194:197], v[4:7], v[162:177]
	ds_read_b128 v[190:193], v16 offset:288
	ds_read_b128 v[242:245], v182 offset:288
	s_waitcnt lgkmcnt(11)
	v_mfma_f32_32x32x16_bf16 v[146:161], v[198:201], v[4:7], v[146:161]
	ds_read_b128 v[246:249], v182 offset:19232
	s_waitcnt lgkmcnt(10)
	v_mfma_f32_32x32x16_bf16 v[162:177], v[202:205], v[8:11], v[162:177]
	ds_read_b128 v[4:7], v16 offset:320
	ds_read_b128 v[194:197], v182 offset:320
	s_waitcnt lgkmcnt(11)
	v_mfma_f32_32x32x16_bf16 v[146:161], v[206:209], v[8:11], v[146:161]
	ds_read_b128 v[198:201], v182 offset:19264
	s_waitcnt lgkmcnt(10)
	v_mfma_f32_32x32x16_bf16 v[162:177], v[210:213], v[12:15], v[162:177]
	ds_read_b128 v[8:11], v16 offset:352
	ds_read_b128 v[202:205], v182 offset:352
	s_waitcnt lgkmcnt(11)
	v_mfma_f32_32x32x16_bf16 v[146:161], v[214:217], v[12:15], v[146:161]
	ds_read_b128 v[206:209], v182 offset:19296
	s_waitcnt lgkmcnt(10)
	v_mfma_f32_32x32x16_bf16 v[162:177], v[234:237], v[186:189], v[162:177]
	ds_read_b128 v[12:15], v16 offset:384
	ds_read_b128 v[210:213], v182 offset:384
	s_waitcnt lgkmcnt(11)
	v_mfma_f32_32x32x16_bf16 v[146:161], v[238:241], v[186:189], v[146:161]
	ds_read_b128 v[214:217], v182 offset:19328
	s_waitcnt lgkmcnt(10)
	v_mfma_f32_32x32x16_bf16 v[162:177], v[242:245], v[190:193], v[162:177]
	ds_read_b128 v[186:189], v16 offset:416
	ds_read_b128 v[234:237], v182 offset:416
	s_waitcnt lgkmcnt(11)
	v_mfma_f32_32x32x16_bf16 v[146:161], v[246:249], v[190:193], v[146:161]
	ds_read_b128 v[238:241], v182 offset:19360
	s_waitcnt lgkmcnt(10)
	v_mfma_f32_32x32x16_bf16 v[162:177], v[194:197], v[4:7], v[162:177]
	ds_read_b128 v[190:193], v16 offset:448
	ds_read_b128 v[242:245], v182 offset:448
	s_waitcnt lgkmcnt(11)
	v_mfma_f32_32x32x16_bf16 v[146:161], v[198:201], v[4:7], v[146:161]
	ds_read_b128 v[246:249], v182 offset:19392
	s_waitcnt lgkmcnt(10)
	v_mfma_f32_32x32x16_bf16 v[162:177], v[202:205], v[8:11], v[162:177]
	ds_read_b128 v[4:7], v16 offset:480
	ds_read_b128 v[194:197], v182 offset:480
	s_waitcnt lgkmcnt(11)
	v_mfma_f32_32x32x16_bf16 v[146:161], v[206:209], v[8:11], v[146:161]
	ds_read_b128 v[198:201], v182 offset:19424
	s_waitcnt lgkmcnt(10)
	v_mfma_f32_32x32x16_bf16 v[162:177], v[210:213], v[12:15], v[162:177]
	ds_read_b128 v[8:11], v16 offset:512
	ds_read_b128 v[202:205], v182 offset:512
	s_waitcnt lgkmcnt(11)
	v_mfma_f32_32x32x16_bf16 v[146:161], v[214:217], v[12:15], v[146:161]
	ds_read_b128 v[206:209], v182 offset:19456
	s_waitcnt lgkmcnt(10)
	v_mfma_f32_32x32x16_bf16 v[162:177], v[234:237], v[186:189], v[162:177]
	ds_read_b128 v[12:15], v16 offset:544
	ds_read_b128 v[210:213], v182 offset:544
	s_waitcnt lgkmcnt(11)
	v_mfma_f32_32x32x16_bf16 v[146:161], v[238:241], v[186:189], v[146:161]
	ds_read_b128 v[214:217], v182 offset:19488
	s_waitcnt lgkmcnt(10)
	v_mfma_f32_32x32x16_bf16 v[162:177], v[242:245], v[190:193], v[162:177]
	s_waitcnt lgkmcnt(9)
	v_mfma_f32_32x32x16_bf16 v[146:161], v[246:249], v[190:193], v[146:161]
	s_waitcnt lgkmcnt(7)
	v_mfma_f32_32x32x16_bf16 v[162:177], v[194:197], v[4:7], v[162:177]
	s_waitcnt lgkmcnt(6)
	v_mfma_f32_32x32x16_bf16 v[146:161], v[198:201], v[4:7], v[146:161]
	s_waitcnt lgkmcnt(4)
	v_mfma_f32_32x32x16_bf16 v[162:177], v[202:205], v[8:11], v[162:177]
	s_waitcnt lgkmcnt(3)
	v_mfma_f32_32x32x16_bf16 v[146:161], v[206:209], v[8:11], v[146:161]
	s_waitcnt lgkmcnt(1)
	v_mfma_f32_32x32x16_bf16 v[162:177], v[210:213], v[12:15], v[162:177]
	s_waitcnt lgkmcnt(0)
	v_mfma_f32_32x32x16_bf16 v[146:161], v[214:217], v[12:15], v[146:161]
	ds_read_b64_tr_b16 v[190:191], v184 offset:0
	ds_read_b64_tr_b16 v[192:193], v184 offset:4736
	ds_read_b64_tr_b16 v[194:195], v184 offset:64
	ds_read_b64_tr_b16 v[196:197], v184 offset:4800
	ds_read_b64_tr_b16 v[198:199], v184 offset:128
	ds_read_b64_tr_b16 v[200:201], v184 offset:4864
	ds_read_b64_tr_b16 v[202:203], v184 offset:192
	ds_read_b64_tr_b16 v[204:205], v184 offset:4928
	ds_read_b64_tr_b16 v[206:207], v184 offset:256
	ds_read_b64_tr_b16 v[208:209], v184 offset:4992
	ds_read_b64_tr_b16 v[210:211], v184 offset:320
	ds_read_b64_tr_b16 v[212:213], v184 offset:5056
	ds_read_b64_tr_b16 v[214:215], v184 offset:384
	ds_read_b64_tr_b16 v[216:217], v184 offset:5120
	v_max3_f32 v2, v162, v146, v163
	v_max3_f32 v17, v147, v164, v148
	v_max3_f32 v2, v2, v165, v149
	v_max3_f32 v17, v17, v166, v150
	v_max3_f32 v2, v2, v167, v151
	v_max3_f32 v17, v17, v168, v152
	v_max3_f32 v2, v2, v169, v153
	v_max3_f32 v17, v17, v170, v154
	v_max3_f32 v2, v2, v171, v155
	v_max3_f32 v17, v17, v172, v156
	v_max3_f32 v2, v2, v173, v157
	v_max3_f32 v17, v17, v174, v158
	v_max3_f32 v2, v2, v175, v159
	v_max3_f32 v17, v17, v176, v160
	v_max3_f32 v2, v2, v17, v177
	v_max_f32_e32 v2, v2, v161
	v_mov_b32_e32 v218, v2
	v_add_f32_e32 v233, 0x41000000, v178
	v_mov_b32_e32 v254, 0
	v_permlane32_swap_b32_e32 v2, v218
	v_max_f32_e32 v2, v2, v218
	v_mul_f32_e32 v2, 0x3e16c740, v2
	v_cmp_gt_f32_e32 vcc, v2, v233
	s_cbranch_vccz .Ldc1_nr0
	v_max_f32_e32 v2, v178, v2
	v_sub_f32_e32 v219, v178, v2
	v_exp_f32_e32 v219, v219
	v_mov_b32_e32 v178, v2
	v_mov_b32_e32 v218, v2
	v_mul_f32_e32 v183, v183, v219
	v_mul_f32_e32 v130, v130, v219
	v_mul_f32_e32 v131, v131, v219
	v_mul_f32_e32 v132, v132, v219
	v_mul_f32_e32 v133, v133, v219
	v_mul_f32_e32 v134, v134, v219
	v_mul_f32_e32 v135, v135, v219
	v_mul_f32_e32 v136, v136, v219
	v_mul_f32_e32 v137, v137, v219
	v_mul_f32_e32 v138, v138, v219
	v_mul_f32_e32 v139, v139, v219
	v_mul_f32_e32 v140, v140, v219
	v_mul_f32_e32 v141, v141, v219
	v_mul_f32_e32 v142, v142, v219
	v_mul_f32_e32 v143, v143, v219
	v_mul_f32_e32 v144, v144, v219
	v_mul_f32_e32 v145, v145, v219
	v_mul_f32_e32 v114, v114, v219
	v_mul_f32_e32 v115, v115, v219
	v_mul_f32_e32 v116, v116, v219
	v_mul_f32_e32 v117, v117, v219
	v_mul_f32_e32 v118, v118, v219
	v_mul_f32_e32 v119, v119, v219
	v_mul_f32_e32 v120, v120, v219
	v_mul_f32_e32 v121, v121, v219
	v_mul_f32_e32 v122, v122, v219
	v_mul_f32_e32 v123, v123, v219
	v_mul_f32_e32 v124, v124, v219
	v_mul_f32_e32 v125, v125, v219
	v_mul_f32_e32 v126, v126, v219
	v_mul_f32_e32 v127, v127, v219
	v_mul_f32_e32 v128, v128, v219
	v_mul_f32_e32 v129, v129, v219
	v_mul_f32_e32 v98, v98, v219
	v_mul_f32_e32 v99, v99, v219
	v_mul_f32_e32 v100, v100, v219
	v_mul_f32_e32 v101, v101, v219
	v_mul_f32_e32 v102, v102, v219
	v_mul_f32_e32 v103, v103, v219
	v_mul_f32_e32 v104, v104, v219
	v_mul_f32_e32 v105, v105, v219
	v_mul_f32_e32 v106, v106, v219
	v_mul_f32_e32 v107, v107, v219
	v_mul_f32_e32 v108, v108, v219
	v_mul_f32_e32 v109, v109, v219
	v_mul_f32_e32 v110, v110, v219
	v_mul_f32_e32 v111, v111, v219
	v_mul_f32_e32 v112, v112, v219
	v_mul_f32_e32 v113, v113, v219
	v_mul_f32_e32 v82, v82, v219
	v_mul_f32_e32 v83, v83, v219
	v_mul_f32_e32 v84, v84, v219
	v_mul_f32_e32 v85, v85, v219
	v_mul_f32_e32 v86, v86, v219
	v_mul_f32_e32 v87, v87, v219
	v_mul_f32_e32 v88, v88, v219
	v_mul_f32_e32 v89, v89, v219
	v_mul_f32_e32 v90, v90, v219
	v_mul_f32_e32 v91, v91, v219
	v_mul_f32_e32 v92, v92, v219
	v_mul_f32_e32 v93, v93, v219
	v_mul_f32_e32 v94, v94, v219
	v_mul_f32_e32 v95, v95, v219
	v_mul_f32_e32 v96, v96, v219
	v_mul_f32_e32 v97, v97, v219
	v_mul_f32_e32 v66, v66, v219
	v_mul_f32_e32 v67, v67, v219
	v_mul_f32_e32 v68, v68, v219
	v_mul_f32_e32 v69, v69, v219
	v_mul_f32_e32 v70, v70, v219
	v_mul_f32_e32 v71, v71, v219
	v_mul_f32_e32 v72, v72, v219
	v_mul_f32_e32 v73, v73, v219
	v_mul_f32_e32 v74, v74, v219
	v_mul_f32_e32 v75, v75, v219
	v_mul_f32_e32 v76, v76, v219
	v_mul_f32_e32 v77, v77, v219
	v_mul_f32_e32 v78, v78, v219
	v_mul_f32_e32 v79, v79, v219
	v_mul_f32_e32 v80, v80, v219
	v_mul_f32_e32 v81, v81, v219
	v_mul_f32_e32 v50, v50, v219
	v_mul_f32_e32 v51, v51, v219
	v_mul_f32_e32 v52, v52, v219
	v_mul_f32_e32 v53, v53, v219
	v_mul_f32_e32 v54, v54, v219
	v_mul_f32_e32 v55, v55, v219
	v_mul_f32_e32 v56, v56, v219
	v_mul_f32_e32 v57, v57, v219
	v_mul_f32_e32 v58, v58, v219
	v_mul_f32_e32 v59, v59, v219
	v_mul_f32_e32 v60, v60, v219
	v_mul_f32_e32 v61, v61, v219
	v_mul_f32_e32 v62, v62, v219
	v_mul_f32_e32 v63, v63, v219
	v_mul_f32_e32 v64, v64, v219
	v_mul_f32_e32 v65, v65, v219
	v_mul_f32_e32 v34, v34, v219
	v_mul_f32_e32 v35, v35, v219
	v_mul_f32_e32 v36, v36, v219
	v_mul_f32_e32 v37, v37, v219
	v_mul_f32_e32 v38, v38, v219
	v_mul_f32_e32 v39, v39, v219
	v_mul_f32_e32 v40, v40, v219
	v_mul_f32_e32 v41, v41, v219
	v_mul_f32_e32 v42, v42, v219
	v_mul_f32_e32 v43, v43, v219
	v_mul_f32_e32 v44, v44, v219
	v_mul_f32_e32 v45, v45, v219
	v_mul_f32_e32 v46, v46, v219
	v_mul_f32_e32 v47, v47, v219
	v_mul_f32_e32 v48, v48, v219
	v_mul_f32_e32 v49, v49, v219
	v_mul_f32_e32 v18, v18, v219
	v_mul_f32_e32 v19, v19, v219
	v_mul_f32_e32 v20, v20, v219
	v_mul_f32_e32 v21, v21, v219
	v_mul_f32_e32 v22, v22, v219
	v_mul_f32_e32 v23, v23, v219
	v_mul_f32_e32 v24, v24, v219
	v_mul_f32_e32 v25, v25, v219
	v_mul_f32_e32 v26, v26, v219
	v_mul_f32_e32 v27, v27, v219
	v_mul_f32_e32 v28, v28, v219
	v_mul_f32_e32 v29, v29, v219
	v_mul_f32_e32 v30, v30, v219
	v_mul_f32_e32 v31, v31, v219
	v_mul_f32_e32 v32, v32, v219
	v_mul_f32_e32 v33, v33, v219
.Ldc1_nr0:
	v_fma_f32 v162, v162, s72, -v178
	v_fma_f32 v146, v146, s72, -v178
	v_fma_f32 v163, v163, s72, -v178
	v_exp_f32_e32 v162, v162
	v_fma_f32 v147, v147, s72, -v178
	v_exp_f32_e32 v146, v146
	v_fma_f32 v164, v164, s72, -v178
	v_exp_f32_e32 v163, v163
	v_fma_f32 v148, v148, s72, -v178
	v_exp_f32_e32 v147, v147
	v_fma_f32 v165, v165, s72, -v178
	v_add_f32_e32 v218, v162, v146
	v_exp_f32_e32 v164, v164
	v_fma_f32 v149, v149, s72, -v178
	v_exp_f32_e32 v148, v148
	v_cvt_pk_bf16_f32 v4, v162, v163
	v_fma_f32 v166, v166, s72, -v178
	v_add_f32_e32 v233, v163, v147
	v_exp_f32_e32 v165, v165
	v_add_f32_e32 v254, v254, v218
	v_cvt_pk_bf16_f32 v12, v146, v147
	v_fma_f32 v150, v150, s72, -v178
	v_exp_f32_e32 v149, v149
	v_fma_f32 v167, v167, s72, -v178
	v_add_f32_e32 v17, v164, v148
	v_exp_f32_e32 v166, v166
	v_add_f32_e32 v254, v254, v233
	v_fma_f32 v151, v151, s72, -v178
	v_exp_f32_e32 v150, v150
	v_cvt_pk_bf16_f32 v5, v164, v165
	v_fma_f32 v168, v168, s72, -v178
	v_add_f32_e32 v219, v165, v149
	v_exp_f32_e32 v167, v167
	v_add_f32_e32 v254, v254, v17
	v_cvt_pk_bf16_f32 v13, v148, v149
	v_fma_f32 v152, v152, s72, -v178
	v_exp_f32_e32 v151, v151
	v_fma_f32 v169, v169, s72, -v178
	v_add_f32_e32 v218, v166, v150
	v_exp_f32_e32 v168, v168
	v_add_f32_e32 v254, v254, v219
	v_fma_f32 v153, v153, s72, -v178
	v_exp_f32_e32 v152, v152
	v_cvt_pk_bf16_f32 v6, v166, v167
	v_fma_f32 v170, v170, s72, -v178
	v_add_f32_e32 v233, v167, v151
	v_exp_f32_e32 v169, v169
	v_add_f32_e32 v254, v254, v218
	v_cvt_pk_bf16_f32 v14, v150, v151
	v_fma_f32 v154, v154, s72, -v178
	v_exp_f32_e32 v153, v153
	v_fma_f32 v171, v171, s72, -v178
	v_add_f32_e32 v17, v168, v152
	v_exp_f32_e32 v170, v170
	v_add_f32_e32 v254, v254, v233
	v_fma_f32 v155, v155, s72, -v178
	v_exp_f32_e32 v154, v154
	v_cvt_pk_bf16_f32 v7, v168, v169
	v_fma_f32 v172, v172, s72, -v178
	v_add_f32_e32 v219, v169, v153
	v_exp_f32_e32 v171, v171
	v_add_f32_e32 v254, v254, v17
	v_cvt_pk_bf16_f32 v15, v152, v153
	v_fma_f32 v156, v156, s72, -v178
	v_exp_f32_e32 v155, v155
	v_fma_f32 v173, v173, s72, -v178
	v_add_f32_e32 v218, v170, v154
	v_exp_f32_e32 v172, v172
	v_add_f32_e32 v254, v254, v219
	v_fma_f32 v157, v157, s72, -v178
	v_exp_f32_e32 v156, v156
	v_cvt_pk_bf16_f32 v8, v170, v171
	v_fma_f32 v174, v174, s72, -v178
	v_add_f32_e32 v233, v171, v155
	v_exp_f32_e32 v173, v173
	v_add_f32_e32 v254, v254, v218
	v_cvt_pk_bf16_f32 v186, v154, v155
	v_fma_f32 v158, v158, s72, -v178
	v_exp_f32_e32 v157, v157
	v_fma_f32 v175, v175, s72, -v178
	v_add_f32_e32 v17, v172, v156
	v_exp_f32_e32 v174, v174
	v_add_f32_e32 v254, v254, v233
	v_fma_f32 v159, v159, s72, -v178
	v_exp_f32_e32 v158, v158
	v_cvt_pk_bf16_f32 v9, v172, v173
	v_fma_f32 v176, v176, s72, -v178
	v_add_f32_e32 v219, v173, v157
	v_exp_f32_e32 v175, v175
	v_add_f32_e32 v254, v254, v17
	v_cvt_pk_bf16_f32 v187, v156, v157
	v_fma_f32 v160, v160, s72, -v178
	v_exp_f32_e32 v159, v159
	v_fma_f32 v177, v177, s72, -v178
	v_add_f32_e32 v218, v174, v158
	v_exp_f32_e32 v176, v176
	v_add_f32_e32 v254, v254, v219
	v_fma_f32 v161, v161, s72, -v178
	v_exp_f32_e32 v160, v160
	v_cvt_pk_bf16_f32 v10, v174, v175
	v_add_f32_e32 v233, v175, v159
	v_exp_f32_e32 v177, v177
	v_add_f32_e32 v254, v254, v218
	v_cvt_pk_bf16_f32 v188, v158, v159
	v_exp_f32_e32 v161, v161
	v_add_f32_e32 v17, v176, v160
	v_add_f32_e32 v254, v254, v233
	v_cvt_pk_bf16_f32 v11, v176, v177
	v_add_f32_e32 v219, v177, v161
	v_add_f32_e32 v254, v254, v17
	v_cvt_pk_bf16_f32 v189, v160, v161
	v_add_f32_e32 v254, v254, v219
	v_add_f32_e32 v183, v183, v254
	s_waitcnt lgkmcnt(12)
	v_mfma_f32_32x32x16_bf16 v[130:145], v[190:193], v[4:7], v[130:145]
	ds_read_b64_tr_b16 v[234:235], v184 offset:448
	ds_read_b64_tr_b16 v[236:237], v184 offset:5184
	s_waitcnt lgkmcnt(12)
	v_mfma_f32_32x32x16_bf16 v[114:129], v[194:197], v[4:7], v[114:129]
	ds_read_b64_tr_b16 v[238:239], v184 offset:9472
	ds_read_b64_tr_b16 v[240:241], v184 offset:14208
	s_waitcnt lgkmcnt(12)
	v_mfma_f32_32x32x16_bf16 v[98:113], v[198:201], v[4:7], v[98:113]
	ds_read_b64_tr_b16 v[242:243], v184 offset:9536
	ds_read_b64_tr_b16 v[244:245], v184 offset:14272
	s_waitcnt lgkmcnt(12)
	v_mfma_f32_32x32x16_bf16 v[82:97], v[202:205], v[4:7], v[82:97]
	ds_read_b64_tr_b16 v[246:247], v184 offset:9600
	ds_read_b64_tr_b16 v[248:249], v184 offset:14336
	s_waitcnt lgkmcnt(12)
	v_mfma_f32_32x32x16_bf16 v[66:81], v[206:209], v[4:7], v[66:81]
	ds_read_b64_tr_b16 v[250:251], v184 offset:9664
	ds_read_b64_tr_b16 v[252:253], v184 offset:14400
	s_waitcnt lgkmcnt(12)
	v_mfma_f32_32x32x16_bf16 v[50:65], v[210:213], v[4:7], v[50:65]
	ds_read_b64_tr_b16 v[190:191], v184 offset:9728
	ds_read_b64_tr_b16 v[192:193], v184 offset:14464
	s_waitcnt lgkmcnt(12)
	v_mfma_f32_32x32x16_bf16 v[34:49], v[214:217], v[4:7], v[34:49]
	ds_read_b64_tr_b16 v[194:195], v184 offset:9792
	ds_read_b64_tr_b16 v[196:197], v184 offset:14528
	s_waitcnt lgkmcnt(12)
	v_mfma_f32_32x32x16_bf16 v[18:33], v[234:237], v[4:7], v[18:33]
	ds_read_b64_tr_b16 v[198:199], v184 offset:9856
	ds_read_b64_tr_b16 v[200:201], v184 offset:14592
	s_waitcnt lgkmcnt(12)
	v_mfma_f32_32x32x16_bf16 v[130:145], v[238:241], v[8:11], v[130:145]
	ds_read_b64_tr_b16 v[202:203], v184 offset:9920
	ds_read_b64_tr_b16 v[204:205], v184 offset:14656
	s_waitcnt lgkmcnt(12)
	v_mfma_f32_32x32x16_bf16 v[114:129], v[242:245], v[8:11], v[114:129]
	ds_read_b64_tr_b16 v[206:207], v184 offset:18944
	ds_read_b64_tr_b16 v[208:209], v184 offset:23680
	s_waitcnt lgkmcnt(12)
	v_mfma_f32_32x32x16_bf16 v[98:113], v[246:249], v[8:11], v[98:113]
	ds_read_b64_tr_b16 v[210:211], v184 offset:19008
	ds_read_b64_tr_b16 v[212:213], v184 offset:23744
	s_waitcnt lgkmcnt(12)
	v_mfma_f32_32x32x16_bf16 v[82:97], v[250:253], v[8:11], v[82:97]
	ds_read_b64_tr_b16 v[214:215], v184 offset:19072
	ds_read_b64_tr_b16 v[216:217], v184 offset:23808
	s_waitcnt lgkmcnt(12)
	v_mfma_f32_32x32x16_bf16 v[66:81], v[190:193], v[8:11], v[66:81]
	ds_read_b64_tr_b16 v[234:235], v184 offset:19136
	ds_read_b64_tr_b16 v[236:237], v184 offset:23872
	s_waitcnt lgkmcnt(12)
	v_mfma_f32_32x32x16_bf16 v[50:65], v[194:197], v[8:11], v[50:65]
	ds_read_b64_tr_b16 v[238:239], v184 offset:19200
	ds_read_b64_tr_b16 v[240:241], v184 offset:23936
	s_waitcnt lgkmcnt(12)
	v_mfma_f32_32x32x16_bf16 v[34:49], v[198:201], v[8:11], v[34:49]
	ds_read_b64_tr_b16 v[242:243], v184 offset:19264
	ds_read_b64_tr_b16 v[244:245], v184 offset:24000
	s_waitcnt lgkmcnt(12)
	v_mfma_f32_32x32x16_bf16 v[18:33], v[202:205], v[8:11], v[18:33]
	ds_read_b64_tr_b16 v[246:247], v184 offset:19328
	ds_read_b64_tr_b16 v[248:249], v184 offset:24064
	s_waitcnt lgkmcnt(12)
	v_mfma_f32_32x32x16_bf16 v[130:145], v[206:209], v[12:15], v[130:145]
	ds_read_b64_tr_b16 v[250:251], v184 offset:19392
	ds_read_b64_tr_b16 v[252:253], v184 offset:24128
	s_waitcnt lgkmcnt(12)
	v_mfma_f32_32x32x16_bf16 v[114:129], v[210:213], v[12:15], v[114:129]
	ds_read_b64_tr_b16 v[190:191], v184 offset:28416
	ds_read_b64_tr_b16 v[192:193], v184 offset:33152
	s_waitcnt lgkmcnt(12)
	v_mfma_f32_32x32x16_bf16 v[98:113], v[214:217], v[12:15], v[98:113]
	ds_read_b64_tr_b16 v[194:195], v184 offset:28480
	ds_read_b64_tr_b16 v[196:197], v184 offset:33216
	s_waitcnt lgkmcnt(12)
	v_mfma_f32_32x32x16_bf16 v[82:97], v[234:237], v[12:15], v[82:97]
	ds_read_b64_tr_b16 v[198:199], v184 offset:28544
	ds_read_b64_tr_b16 v[200:201], v184 offset:33280
	s_waitcnt lgkmcnt(12)
	v_mfma_f32_32x32x16_bf16 v[66:81], v[238:241], v[12:15], v[66:81]
	ds_read_b64_tr_b16 v[202:203], v184 offset:28608
	ds_read_b64_tr_b16 v[204:205], v184 offset:33344
	s_waitcnt lgkmcnt(12)
	v_mfma_f32_32x32x16_bf16 v[50:65], v[242:245], v[12:15], v[50:65]
	ds_read_b64_tr_b16 v[206:207], v184 offset:28672
	ds_read_b64_tr_b16 v[208:209], v184 offset:33408
	s_waitcnt lgkmcnt(12)
	v_mfma_f32_32x32x16_bf16 v[34:49], v[246:249], v[12:15], v[34:49]
	ds_read_b64_tr_b16 v[210:211], v184 offset:28736
	ds_read_b64_tr_b16 v[212:213], v184 offset:33472
	s_waitcnt lgkmcnt(12)
	v_mfma_f32_32x32x16_bf16 v[18:33], v[250:253], v[12:15], v[18:33]
	ds_read_b64_tr_b16 v[214:215], v184 offset:28800
	ds_read_b64_tr_b16 v[216:217], v184 offset:33536
	s_waitcnt lgkmcnt(12)
	v_mfma_f32_32x32x16_bf16 v[130:145], v[190:193], v[186:189], v[130:145]
	ds_read_b64_tr_b16 v[234:235], v184 offset:28864
	ds_read_b64_tr_b16 v[236:237], v184 offset:33600
	s_waitcnt lgkmcnt(12)
	v_mfma_f32_32x32x16_bf16 v[114:129], v[194:197], v[186:189], v[114:129]
	s_waitcnt lgkmcnt(10)
	v_mfma_f32_32x32x16_bf16 v[98:113], v[198:201], v[186:189], v[98:113]
	s_waitcnt lgkmcnt(8)
	v_mfma_f32_32x32x16_bf16 v[82:97], v[202:205], v[186:189], v[82:97]
	s_waitcnt lgkmcnt(6)
	v_mfma_f32_32x32x16_bf16 v[66:81], v[206:209], v[186:189], v[66:81]
	s_waitcnt lgkmcnt(4)
	v_mfma_f32_32x32x16_bf16 v[50:65], v[210:213], v[186:189], v[50:65]
	s_waitcnt lgkmcnt(2)
	v_mfma_f32_32x32x16_bf16 v[34:49], v[214:217], v[186:189], v[34:49]
	s_waitcnt lgkmcnt(0)
	v_mfma_f32_32x32x16_bf16 v[18:33], v[234:237], v[186:189], v[18:33]
	s_waitcnt lgkmcnt(0)
	s_barrier
	ds_read_b128 v[4:7], v16 offset:0
	ds_read_b128 v[194:197], v182 offset:37888
	ds_read_b128 v[198:201], v182 offset:56832
	ds_read_b128 v[8:11], v16 offset:32
	ds_read_b128 v[202:205], v182 offset:37920
	ds_read_b128 v[206:209], v182 offset:56864
	ds_read_b128 v[12:15], v16 offset:64
	ds_read_b128 v[210:213], v182 offset:37952
	ds_read_b128 v[214:217], v182 offset:56896
	s_waitcnt lgkmcnt(7)
	v_mfma_f32_32x32x16_bf16 v[162:177], v[194:197], v[4:7], 0
	ds_read_b128 v[186:189], v16 offset:96
	ds_read_b128 v[234:237], v182 offset:37984
	ds_read_b128 v[238:241], v182 offset:56928
	ds_read_b128 v[190:193], v16 offset:128
	ds_read_b128 v[242:245], v182 offset:38016
	s_waitcnt lgkmcnt(11)
	v_mfma_f32_32x32x16_bf16 v[146:161], v[198:201], v[4:7], 0
	ds_read_b128 v[246:249], v182 offset:56960
	s_waitcnt lgkmcnt(10)
	v_mfma_f32_32x32x16_bf16 v[162:177], v[202:205], v[8:11], v[162:177]
	ds_read_b128 v[4:7], v16 offset:160
	ds_read_b128 v[194:197], v182 offset:38048
	s_waitcnt lgkmcnt(11)
	v_mfma_f32_32x32x16_bf16 v[146:161], v[206:209], v[8:11], v[146:161]
	ds_read_b128 v[198:201], v182 offset:56992
	s_waitcnt lgkmcnt(10)
	v_mfma_f32_32x32x16_bf16 v[162:177], v[210:213], v[12:15], v[162:177]
	ds_read_b128 v[8:11], v16 offset:192
	ds_read_b128 v[202:205], v182 offset:38080
	s_waitcnt lgkmcnt(11)
	v_mfma_f32_32x32x16_bf16 v[146:161], v[214:217], v[12:15], v[146:161]
	ds_read_b128 v[206:209], v182 offset:57024
	s_waitcnt lgkmcnt(10)
	v_mfma_f32_32x32x16_bf16 v[162:177], v[234:237], v[186:189], v[162:177]
	ds_read_b128 v[12:15], v16 offset:224
	ds_read_b128 v[210:213], v182 offset:38112
	s_waitcnt lgkmcnt(11)
	v_mfma_f32_32x32x16_bf16 v[146:161], v[238:241], v[186:189], v[146:161]
	ds_read_b128 v[214:217], v182 offset:57056
	s_waitcnt lgkmcnt(10)
	v_mfma_f32_32x32x16_bf16 v[162:177], v[242:245], v[190:193], v[162:177]
	ds_read_b128 v[186:189], v16 offset:256
	ds_read_b128 v[234:237], v182 offset:38144
	s_waitcnt lgkmcnt(11)
	v_mfma_f32_32x32x16_bf16 v[146:161], v[246:249], v[190:193], v[146:161]
	ds_read_b128 v[238:241], v182 offset:57088
	s_waitcnt lgkmcnt(10)
	v_mfma_f32_32x32x16_bf16 v[162:177], v[194:197], v[4:7], v[162:177]
	ds_read_b128 v[190:193], v16 offset:288
	ds_read_b128 v[242:245], v182 offset:38176
	s_waitcnt lgkmcnt(11)
	v_mfma_f32_32x32x16_bf16 v[146:161], v[198:201], v[4:7], v[146:161]
	ds_read_b128 v[246:249], v182 offset:57120
	s_waitcnt lgkmcnt(10)
	v_mfma_f32_32x32x16_bf16 v[162:177], v[202:205], v[8:11], v[162:177]
	ds_read_b128 v[4:7], v16 offset:320
	ds_read_b128 v[194:197], v182 offset:38208
	s_waitcnt lgkmcnt(11)
	v_mfma_f32_32x32x16_bf16 v[146:161], v[206:209], v[8:11], v[146:161]
	ds_read_b128 v[198:201], v182 offset:57152
	s_waitcnt lgkmcnt(10)
	v_mfma_f32_32x32x16_bf16 v[162:177], v[210:213], v[12:15], v[162:177]
	ds_read_b128 v[8:11], v16 offset:352
	ds_read_b128 v[202:205], v182 offset:38240
	s_waitcnt lgkmcnt(11)
	v_mfma_f32_32x32x16_bf16 v[146:161], v[214:217], v[12:15], v[146:161]
	ds_read_b128 v[206:209], v182 offset:57184
	s_waitcnt lgkmcnt(10)
	v_mfma_f32_32x32x16_bf16 v[162:177], v[234:237], v[186:189], v[162:177]
	ds_read_b128 v[12:15], v16 offset:384
	ds_read_b128 v[210:213], v182 offset:38272
	s_waitcnt lgkmcnt(11)
	v_mfma_f32_32x32x16_bf16 v[146:161], v[238:241], v[186:189], v[146:161]
	ds_read_b128 v[214:217], v182 offset:57216
	s_waitcnt lgkmcnt(10)
	v_mfma_f32_32x32x16_bf16 v[162:177], v[242:245], v[190:193], v[162:177]
	ds_read_b128 v[186:189], v16 offset:416
	ds_read_b128 v[234:237], v182 offset:38304
	s_waitcnt lgkmcnt(11)
	v_mfma_f32_32x32x16_bf16 v[146:161], v[246:249], v[190:193], v[146:161]
	ds_read_b128 v[238:241], v182 offset:57248
	s_waitcnt lgkmcnt(10)
	v_mfma_f32_32x32x16_bf16 v[162:177], v[194:197], v[4:7], v[162:177]
	ds_read_b128 v[190:193], v16 offset:448
	ds_read_b128 v[242:245], v182 offset:38336
	s_waitcnt lgkmcnt(11)
	v_mfma_f32_32x32x16_bf16 v[146:161], v[198:201], v[4:7], v[146:161]
	ds_read_b128 v[246:249], v182 offset:57280
	s_waitcnt lgkmcnt(10)
	v_mfma_f32_32x32x16_bf16 v[162:177], v[202:205], v[8:11], v[162:177]
	ds_read_b128 v[4:7], v16 offset:480
	ds_read_b128 v[194:197], v182 offset:38368
	s_waitcnt lgkmcnt(11)
	v_mfma_f32_32x32x16_bf16 v[146:161], v[206:209], v[8:11], v[146:161]
	ds_read_b128 v[198:201], v182 offset:57312
	s_waitcnt lgkmcnt(10)
	v_mfma_f32_32x32x16_bf16 v[162:177], v[210:213], v[12:15], v[162:177]
	ds_read_b128 v[8:11], v16 offset:512
	ds_read_b128 v[202:205], v182 offset:38400
	s_waitcnt lgkmcnt(11)
	v_mfma_f32_32x32x16_bf16 v[146:161], v[214:217], v[12:15], v[146:161]
	ds_read_b128 v[206:209], v182 offset:57344
	s_waitcnt lgkmcnt(10)
	v_mfma_f32_32x32x16_bf16 v[162:177], v[234:237], v[186:189], v[162:177]
	ds_read_b128 v[12:15], v16 offset:544
	ds_read_b128 v[210:213], v182 offset:38432
	s_waitcnt lgkmcnt(11)
	v_mfma_f32_32x32x16_bf16 v[146:161], v[238:241], v[186:189], v[146:161]
	ds_read_b128 v[214:217], v182 offset:57376
	s_waitcnt lgkmcnt(10)
	v_mfma_f32_32x32x16_bf16 v[162:177], v[242:245], v[190:193], v[162:177]
	s_waitcnt lgkmcnt(9)
	v_mfma_f32_32x32x16_bf16 v[146:161], v[246:249], v[190:193], v[146:161]
	s_waitcnt lgkmcnt(7)
	v_mfma_f32_32x32x16_bf16 v[162:177], v[194:197], v[4:7], v[162:177]
	s_waitcnt lgkmcnt(6)
	v_mfma_f32_32x32x16_bf16 v[146:161], v[198:201], v[4:7], v[146:161]
	s_waitcnt lgkmcnt(4)
	v_mfma_f32_32x32x16_bf16 v[162:177], v[202:205], v[8:11], v[162:177]
	s_waitcnt lgkmcnt(3)
	v_mfma_f32_32x32x16_bf16 v[146:161], v[206:209], v[8:11], v[146:161]
	s_waitcnt lgkmcnt(1)
	v_mfma_f32_32x32x16_bf16 v[162:177], v[210:213], v[12:15], v[162:177]
	s_waitcnt lgkmcnt(0)
	v_mfma_f32_32x32x16_bf16 v[146:161], v[214:217], v[12:15], v[146:161]
	ds_read_b64_tr_b16 v[190:191], v185 offset:0
	ds_read_b64_tr_b16 v[192:193], v185 offset:4736
	ds_read_b64_tr_b16 v[194:195], v185 offset:64
	ds_read_b64_tr_b16 v[196:197], v185 offset:4800
	ds_read_b64_tr_b16 v[198:199], v185 offset:128
	ds_read_b64_tr_b16 v[200:201], v185 offset:4864
	ds_read_b64_tr_b16 v[202:203], v185 offset:192
	ds_read_b64_tr_b16 v[204:205], v185 offset:4928
	ds_read_b64_tr_b16 v[206:207], v185 offset:256
	ds_read_b64_tr_b16 v[208:209], v185 offset:4992
	ds_read_b64_tr_b16 v[210:211], v185 offset:320
	ds_read_b64_tr_b16 v[212:213], v185 offset:5056
	ds_read_b64_tr_b16 v[214:215], v185 offset:384
	ds_read_b64_tr_b16 v[216:217], v185 offset:5120
	v_max3_f32 v2, v162, v146, v163
	v_max3_f32 v17, v147, v164, v148
	v_max3_f32 v2, v2, v165, v149
	v_max3_f32 v17, v17, v166, v150
	v_max3_f32 v2, v2, v167, v151
	v_max3_f32 v17, v17, v168, v152
	v_max3_f32 v2, v2, v169, v153
	v_max3_f32 v17, v17, v170, v154
	v_max3_f32 v2, v2, v171, v155
	v_max3_f32 v17, v17, v172, v156
	v_max3_f32 v2, v2, v173, v157
	v_max3_f32 v17, v17, v174, v158
	v_max3_f32 v2, v2, v175, v159
	v_max3_f32 v17, v17, v176, v160
	v_max3_f32 v2, v2, v17, v177
	v_max_f32_e32 v2, v2, v161
	v_mov_b32_e32 v218, v2
	v_add_f32_e32 v233, 0x41000000, v178
	v_mov_b32_e32 v254, 0
	v_permlane32_swap_b32_e32 v2, v218
	v_max_f32_e32 v2, v2, v218
	v_mul_f32_e32 v2, 0x3e16c740, v2
	v_cmp_gt_f32_e32 vcc, v2, v233
	s_cbranch_vccz .Ldc1_nr1
	v_max_f32_e32 v2, v178, v2
	v_sub_f32_e32 v219, v178, v2
	v_exp_f32_e32 v219, v219
	v_mov_b32_e32 v178, v2
	v_mov_b32_e32 v218, v2
	v_mul_f32_e32 v183, v183, v219
	v_mul_f32_e32 v130, v130, v219
	v_mul_f32_e32 v131, v131, v219
	v_mul_f32_e32 v132, v132, v219
	v_mul_f32_e32 v133, v133, v219
	v_mul_f32_e32 v134, v134, v219
	v_mul_f32_e32 v135, v135, v219
	v_mul_f32_e32 v136, v136, v219
	v_mul_f32_e32 v137, v137, v219
	v_mul_f32_e32 v138, v138, v219
	v_mul_f32_e32 v139, v139, v219
	v_mul_f32_e32 v140, v140, v219
	v_mul_f32_e32 v141, v141, v219
	v_mul_f32_e32 v142, v142, v219
	v_mul_f32_e32 v143, v143, v219
	v_mul_f32_e32 v144, v144, v219
	v_mul_f32_e32 v145, v145, v219
	v_mul_f32_e32 v114, v114, v219
	v_mul_f32_e32 v115, v115, v219
	v_mul_f32_e32 v116, v116, v219
	v_mul_f32_e32 v117, v117, v219
	v_mul_f32_e32 v118, v118, v219
	v_mul_f32_e32 v119, v119, v219
	v_mul_f32_e32 v120, v120, v219
	v_mul_f32_e32 v121, v121, v219
	v_mul_f32_e32 v122, v122, v219
	v_mul_f32_e32 v123, v123, v219
	v_mul_f32_e32 v124, v124, v219
	v_mul_f32_e32 v125, v125, v219
	v_mul_f32_e32 v126, v126, v219
	v_mul_f32_e32 v127, v127, v219
	v_mul_f32_e32 v128, v128, v219
	v_mul_f32_e32 v129, v129, v219
	v_mul_f32_e32 v98, v98, v219
	v_mul_f32_e32 v99, v99, v219
	v_mul_f32_e32 v100, v100, v219
	v_mul_f32_e32 v101, v101, v219
	v_mul_f32_e32 v102, v102, v219
	v_mul_f32_e32 v103, v103, v219
	v_mul_f32_e32 v104, v104, v219
	v_mul_f32_e32 v105, v105, v219
	v_mul_f32_e32 v106, v106, v219
	v_mul_f32_e32 v107, v107, v219
	v_mul_f32_e32 v108, v108, v219
	v_mul_f32_e32 v109, v109, v219
	v_mul_f32_e32 v110, v110, v219
	v_mul_f32_e32 v111, v111, v219
	v_mul_f32_e32 v112, v112, v219
	v_mul_f32_e32 v113, v113, v219
	v_mul_f32_e32 v82, v82, v219
	v_mul_f32_e32 v83, v83, v219
	v_mul_f32_e32 v84, v84, v219
	v_mul_f32_e32 v85, v85, v219
	v_mul_f32_e32 v86, v86, v219
	v_mul_f32_e32 v87, v87, v219
	v_mul_f32_e32 v88, v88, v219
	v_mul_f32_e32 v89, v89, v219
	v_mul_f32_e32 v90, v90, v219
	v_mul_f32_e32 v91, v91, v219
	v_mul_f32_e32 v92, v92, v219
	v_mul_f32_e32 v93, v93, v219
	v_mul_f32_e32 v94, v94, v219
	v_mul_f32_e32 v95, v95, v219
	v_mul_f32_e32 v96, v96, v219
	v_mul_f32_e32 v97, v97, v219
	v_mul_f32_e32 v66, v66, v219
	v_mul_f32_e32 v67, v67, v219
	v_mul_f32_e32 v68, v68, v219
	v_mul_f32_e32 v69, v69, v219
	v_mul_f32_e32 v70, v70, v219
	v_mul_f32_e32 v71, v71, v219
	v_mul_f32_e32 v72, v72, v219
	v_mul_f32_e32 v73, v73, v219
	v_mul_f32_e32 v74, v74, v219
	v_mul_f32_e32 v75, v75, v219
	v_mul_f32_e32 v76, v76, v219
	v_mul_f32_e32 v77, v77, v219
	v_mul_f32_e32 v78, v78, v219
	v_mul_f32_e32 v79, v79, v219
	v_mul_f32_e32 v80, v80, v219
	v_mul_f32_e32 v81, v81, v219
	v_mul_f32_e32 v50, v50, v219
	v_mul_f32_e32 v51, v51, v219
	v_mul_f32_e32 v52, v52, v219
	v_mul_f32_e32 v53, v53, v219
	v_mul_f32_e32 v54, v54, v219
	v_mul_f32_e32 v55, v55, v219
	v_mul_f32_e32 v56, v56, v219
	v_mul_f32_e32 v57, v57, v219
	v_mul_f32_e32 v58, v58, v219
	v_mul_f32_e32 v59, v59, v219
	v_mul_f32_e32 v60, v60, v219
	v_mul_f32_e32 v61, v61, v219
	v_mul_f32_e32 v62, v62, v219
	v_mul_f32_e32 v63, v63, v219
	v_mul_f32_e32 v64, v64, v219
	v_mul_f32_e32 v65, v65, v219
	v_mul_f32_e32 v34, v34, v219
	v_mul_f32_e32 v35, v35, v219
	v_mul_f32_e32 v36, v36, v219
	v_mul_f32_e32 v37, v37, v219
	v_mul_f32_e32 v38, v38, v219
	v_mul_f32_e32 v39, v39, v219
	v_mul_f32_e32 v40, v40, v219
	v_mul_f32_e32 v41, v41, v219
	v_mul_f32_e32 v42, v42, v219
	v_mul_f32_e32 v43, v43, v219
	v_mul_f32_e32 v44, v44, v219
	v_mul_f32_e32 v45, v45, v219
	v_mul_f32_e32 v46, v46, v219
	v_mul_f32_e32 v47, v47, v219
	v_mul_f32_e32 v48, v48, v219
	v_mul_f32_e32 v49, v49, v219
	v_mul_f32_e32 v18, v18, v219
	v_mul_f32_e32 v19, v19, v219
	v_mul_f32_e32 v20, v20, v219
	v_mul_f32_e32 v21, v21, v219
	v_mul_f32_e32 v22, v22, v219
	v_mul_f32_e32 v23, v23, v219
	v_mul_f32_e32 v24, v24, v219
	v_mul_f32_e32 v25, v25, v219
	v_mul_f32_e32 v26, v26, v219
	v_mul_f32_e32 v27, v27, v219
	v_mul_f32_e32 v28, v28, v219
	v_mul_f32_e32 v29, v29, v219
	v_mul_f32_e32 v30, v30, v219
	v_mul_f32_e32 v31, v31, v219
	v_mul_f32_e32 v32, v32, v219
	v_mul_f32_e32 v33, v33, v219
.Ldc1_nr1:
	v_fma_f32 v162, v162, s72, -v178
	v_fma_f32 v146, v146, s72, -v178
	v_fma_f32 v163, v163, s72, -v178
	v_exp_f32_e32 v162, v162
	v_fma_f32 v147, v147, s72, -v178
	v_exp_f32_e32 v146, v146
	v_fma_f32 v164, v164, s72, -v178
	v_exp_f32_e32 v163, v163
	v_fma_f32 v148, v148, s72, -v178
	v_exp_f32_e32 v147, v147
	v_fma_f32 v165, v165, s72, -v178
	v_add_f32_e32 v218, v162, v146
	v_exp_f32_e32 v164, v164
	v_fma_f32 v149, v149, s72, -v178
	v_exp_f32_e32 v148, v148
	v_cvt_pk_bf16_f32 v4, v162, v163
	v_fma_f32 v166, v166, s72, -v178
	v_add_f32_e32 v233, v163, v147
	v_exp_f32_e32 v165, v165
	v_add_f32_e32 v254, v254, v218
	v_cvt_pk_bf16_f32 v12, v146, v147
	v_fma_f32 v150, v150, s72, -v178
	v_exp_f32_e32 v149, v149
	v_fma_f32 v167, v167, s72, -v178
	v_add_f32_e32 v17, v164, v148
	v_exp_f32_e32 v166, v166
	v_add_f32_e32 v254, v254, v233
	v_fma_f32 v151, v151, s72, -v178
	v_exp_f32_e32 v150, v150
	v_cvt_pk_bf16_f32 v5, v164, v165
	v_fma_f32 v168, v168, s72, -v178
	v_add_f32_e32 v219, v165, v149
	v_exp_f32_e32 v167, v167
	v_add_f32_e32 v254, v254, v17
	v_cvt_pk_bf16_f32 v13, v148, v149
	v_fma_f32 v152, v152, s72, -v178
	v_exp_f32_e32 v151, v151
	v_fma_f32 v169, v169, s72, -v178
	v_add_f32_e32 v218, v166, v150
	v_exp_f32_e32 v168, v168
	v_add_f32_e32 v254, v254, v219
	v_fma_f32 v153, v153, s72, -v178
	v_exp_f32_e32 v152, v152
	v_cvt_pk_bf16_f32 v6, v166, v167
	v_fma_f32 v170, v170, s72, -v178
	v_add_f32_e32 v233, v167, v151
	v_exp_f32_e32 v169, v169
	v_add_f32_e32 v254, v254, v218
	v_cvt_pk_bf16_f32 v14, v150, v151
	v_fma_f32 v154, v154, s72, -v178
	v_exp_f32_e32 v153, v153
	v_fma_f32 v171, v171, s72, -v178
	v_add_f32_e32 v17, v168, v152
	v_exp_f32_e32 v170, v170
	v_add_f32_e32 v254, v254, v233
	v_fma_f32 v155, v155, s72, -v178
	v_exp_f32_e32 v154, v154
	v_cvt_pk_bf16_f32 v7, v168, v169
	v_fma_f32 v172, v172, s72, -v178
	v_add_f32_e32 v219, v169, v153
	v_exp_f32_e32 v171, v171
	v_add_f32_e32 v254, v254, v17
	v_cvt_pk_bf16_f32 v15, v152, v153
	v_fma_f32 v156, v156, s72, -v178
	v_exp_f32_e32 v155, v155
	v_fma_f32 v173, v173, s72, -v178
	v_add_f32_e32 v218, v170, v154
	v_exp_f32_e32 v172, v172
	v_add_f32_e32 v254, v254, v219
	v_fma_f32 v157, v157, s72, -v178
	v_exp_f32_e32 v156, v156
	v_cvt_pk_bf16_f32 v8, v170, v171
	v_fma_f32 v174, v174, s72, -v178
	v_add_f32_e32 v233, v171, v155
	v_exp_f32_e32 v173, v173
	v_add_f32_e32 v254, v254, v218
	v_cvt_pk_bf16_f32 v186, v154, v155
	v_fma_f32 v158, v158, s72, -v178
	v_exp_f32_e32 v157, v157
	v_fma_f32 v175, v175, s72, -v178
	v_add_f32_e32 v17, v172, v156
	v_exp_f32_e32 v174, v174
	v_add_f32_e32 v254, v254, v233
	v_fma_f32 v159, v159, s72, -v178
	v_exp_f32_e32 v158, v158
	v_cvt_pk_bf16_f32 v9, v172, v173
	v_fma_f32 v176, v176, s72, -v178
	v_add_f32_e32 v219, v173, v157
	v_exp_f32_e32 v175, v175
	v_add_f32_e32 v254, v254, v17
	v_cvt_pk_bf16_f32 v187, v156, v157
	v_fma_f32 v160, v160, s72, -v178
	v_exp_f32_e32 v159, v159
	v_fma_f32 v177, v177, s72, -v178
	v_add_f32_e32 v218, v174, v158
	v_exp_f32_e32 v176, v176
	v_add_f32_e32 v254, v254, v219
	v_fma_f32 v161, v161, s72, -v178
	v_exp_f32_e32 v160, v160
	v_cvt_pk_bf16_f32 v10, v174, v175
	v_add_f32_e32 v233, v175, v159
	v_exp_f32_e32 v177, v177
	v_add_f32_e32 v254, v254, v218
	v_cvt_pk_bf16_f32 v188, v158, v159
	v_exp_f32_e32 v161, v161
	v_add_f32_e32 v17, v176, v160
	v_add_f32_e32 v254, v254, v233
	v_cvt_pk_bf16_f32 v11, v176, v177
	v_add_f32_e32 v219, v177, v161
	v_add_f32_e32 v254, v254, v17
	v_cvt_pk_bf16_f32 v189, v160, v161
	v_add_f32_e32 v254, v254, v219
	v_add_f32_e32 v183, v183, v254
	s_waitcnt lgkmcnt(12)
	v_mfma_f32_32x32x16_bf16 v[130:145], v[190:193], v[4:7], v[130:145]
	ds_read_b64_tr_b16 v[234:235], v185 offset:448
	ds_read_b64_tr_b16 v[236:237], v185 offset:5184
	s_waitcnt lgkmcnt(12)
	v_mfma_f32_32x32x16_bf16 v[114:129], v[194:197], v[4:7], v[114:129]
	ds_read_b64_tr_b16 v[238:239], v185 offset:9472
	ds_read_b64_tr_b16 v[240:241], v185 offset:14208
	s_waitcnt lgkmcnt(12)
	v_mfma_f32_32x32x16_bf16 v[98:113], v[198:201], v[4:7], v[98:113]
	ds_read_b64_tr_b16 v[242:243], v185 offset:9536
	ds_read_b64_tr_b16 v[244:245], v185 offset:14272
	s_waitcnt lgkmcnt(12)
	v_mfma_f32_32x32x16_bf16 v[82:97], v[202:205], v[4:7], v[82:97]
	ds_read_b64_tr_b16 v[246:247], v185 offset:9600
	ds_read_b64_tr_b16 v[248:249], v185 offset:14336
	s_waitcnt lgkmcnt(12)
	v_mfma_f32_32x32x16_bf16 v[66:81], v[206:209], v[4:7], v[66:81]
	ds_read_b64_tr_b16 v[250:251], v185 offset:9664
	ds_read_b64_tr_b16 v[252:253], v185 offset:14400
	s_waitcnt lgkmcnt(12)
	v_mfma_f32_32x32x16_bf16 v[50:65], v[210:213], v[4:7], v[50:65]
	ds_read_b64_tr_b16 v[190:191], v185 offset:9728
	ds_read_b64_tr_b16 v[192:193], v185 offset:14464
	s_waitcnt lgkmcnt(12)
	v_mfma_f32_32x32x16_bf16 v[34:49], v[214:217], v[4:7], v[34:49]
	ds_read_b64_tr_b16 v[194:195], v185 offset:9792
	ds_read_b64_tr_b16 v[196:197], v185 offset:14528
	s_waitcnt lgkmcnt(12)
	v_mfma_f32_32x32x16_bf16 v[18:33], v[234:237], v[4:7], v[18:33]
	ds_read_b64_tr_b16 v[198:199], v185 offset:9856
	ds_read_b64_tr_b16 v[200:201], v185 offset:14592
	s_waitcnt lgkmcnt(12)
	v_mfma_f32_32x32x16_bf16 v[130:145], v[238:241], v[8:11], v[130:145]
	ds_read_b64_tr_b16 v[202:203], v185 offset:9920
	ds_read_b64_tr_b16 v[204:205], v185 offset:14656
	s_waitcnt lgkmcnt(12)
	v_mfma_f32_32x32x16_bf16 v[114:129], v[242:245], v[8:11], v[114:129]
	ds_read_b64_tr_b16 v[206:207], v185 offset:18944
	ds_read_b64_tr_b16 v[208:209], v185 offset:23680
	s_waitcnt lgkmcnt(12)
	v_mfma_f32_32x32x16_bf16 v[98:113], v[246:249], v[8:11], v[98:113]
	ds_read_b64_tr_b16 v[210:211], v185 offset:19008
	ds_read_b64_tr_b16 v[212:213], v185 offset:23744
	s_waitcnt lgkmcnt(12)
	v_mfma_f32_32x32x16_bf16 v[82:97], v[250:253], v[8:11], v[82:97]
	ds_read_b64_tr_b16 v[214:215], v185 offset:19072
	ds_read_b64_tr_b16 v[216:217], v185 offset:23808
	s_waitcnt lgkmcnt(12)
	v_mfma_f32_32x32x16_bf16 v[66:81], v[190:193], v[8:11], v[66:81]
	ds_read_b64_tr_b16 v[234:235], v185 offset:19136
	ds_read_b64_tr_b16 v[236:237], v185 offset:23872
	s_waitcnt lgkmcnt(12)
	v_mfma_f32_32x32x16_bf16 v[50:65], v[194:197], v[8:11], v[50:65]
	ds_read_b64_tr_b16 v[238:239], v185 offset:19200
	ds_read_b64_tr_b16 v[240:241], v185 offset:23936
	s_waitcnt lgkmcnt(12)
	v_mfma_f32_32x32x16_bf16 v[34:49], v[198:201], v[8:11], v[34:49]
	ds_read_b64_tr_b16 v[242:243], v185 offset:19264
	ds_read_b64_tr_b16 v[244:245], v185 offset:24000
	s_waitcnt lgkmcnt(12)
	v_mfma_f32_32x32x16_bf16 v[18:33], v[202:205], v[8:11], v[18:33]
	ds_read_b64_tr_b16 v[246:247], v185 offset:19328
	ds_read_b64_tr_b16 v[248:249], v185 offset:24064
	s_waitcnt lgkmcnt(12)
	v_mfma_f32_32x32x16_bf16 v[130:145], v[206:209], v[12:15], v[130:145]
	ds_read_b64_tr_b16 v[250:251], v185 offset:19392
	ds_read_b64_tr_b16 v[252:253], v185 offset:24128
	s_waitcnt lgkmcnt(12)
	v_mfma_f32_32x32x16_bf16 v[114:129], v[210:213], v[12:15], v[114:129]
	ds_read_b64_tr_b16 v[190:191], v185 offset:28416
	ds_read_b64_tr_b16 v[192:193], v185 offset:33152
	s_waitcnt lgkmcnt(12)
	v_mfma_f32_32x32x16_bf16 v[98:113], v[214:217], v[12:15], v[98:113]
	ds_read_b64_tr_b16 v[194:195], v185 offset:28480
	ds_read_b64_tr_b16 v[196:197], v185 offset:33216
	s_waitcnt lgkmcnt(12)
	v_mfma_f32_32x32x16_bf16 v[82:97], v[234:237], v[12:15], v[82:97]
	ds_read_b64_tr_b16 v[198:199], v185 offset:28544
	ds_read_b64_tr_b16 v[200:201], v185 offset:33280
	s_waitcnt lgkmcnt(12)
	v_mfma_f32_32x32x16_bf16 v[66:81], v[238:241], v[12:15], v[66:81]
	ds_read_b64_tr_b16 v[202:203], v185 offset:28608
	ds_read_b64_tr_b16 v[204:205], v185 offset:33344
	s_waitcnt lgkmcnt(12)
	v_mfma_f32_32x32x16_bf16 v[50:65], v[242:245], v[12:15], v[50:65]
	ds_read_b64_tr_b16 v[206:207], v185 offset:28672
	ds_read_b64_tr_b16 v[208:209], v185 offset:33408
	s_waitcnt lgkmcnt(12)
	v_mfma_f32_32x32x16_bf16 v[34:49], v[246:249], v[12:15], v[34:49]
	ds_read_b64_tr_b16 v[210:211], v185 offset:28736
	ds_read_b64_tr_b16 v[212:213], v185 offset:33472
	s_waitcnt lgkmcnt(12)
	v_mfma_f32_32x32x16_bf16 v[18:33], v[250:253], v[12:15], v[18:33]
	ds_read_b64_tr_b16 v[214:215], v185 offset:28800
	ds_read_b64_tr_b16 v[216:217], v185 offset:33536
	s_waitcnt lgkmcnt(12)
	v_mfma_f32_32x32x16_bf16 v[130:145], v[190:193], v[186:189], v[130:145]
	ds_read_b64_tr_b16 v[234:235], v185 offset:28864
	ds_read_b64_tr_b16 v[236:237], v185 offset:33600
	s_waitcnt lgkmcnt(12)
	v_mfma_f32_32x32x16_bf16 v[114:129], v[194:197], v[186:189], v[114:129]
	s_waitcnt lgkmcnt(10)
	v_mfma_f32_32x32x16_bf16 v[98:113], v[198:201], v[186:189], v[98:113]
	s_waitcnt lgkmcnt(8)
	v_mfma_f32_32x32x16_bf16 v[82:97], v[202:205], v[186:189], v[82:97]
	s_waitcnt lgkmcnt(6)
	v_mfma_f32_32x32x16_bf16 v[66:81], v[206:209], v[186:189], v[66:81]
	s_waitcnt lgkmcnt(4)
	v_mfma_f32_32x32x16_bf16 v[50:65], v[210:213], v[186:189], v[50:65]
	s_waitcnt lgkmcnt(2)
	v_mfma_f32_32x32x16_bf16 v[34:49], v[214:217], v[186:189], v[34:49]
	s_waitcnt lgkmcnt(0)
	v_mfma_f32_32x32x16_bf16 v[18:33], v[234:237], v[186:189], v[18:33]
	s_waitcnt lgkmcnt(0)
	s_barrier
	s_add_i32 s22, s22, 2
	s_cmp_gt_u32 s22, 61
	s_cbranch_scc0 .LBB0_836
	s_branch .LBB0_841

.LBB0_911:
	v_add_u32_e32 v16, s50, v182
	ds_read_b128 v[4:7], v16 offset:0
	ds_read_b128 v[194:197], v182 offset:0
	ds_read_b128 v[198:201], v182 offset:18944
	ds_read_b128 v[8:11], v16 offset:32
	ds_read_b128 v[202:205], v182 offset:32
	ds_read_b128 v[206:209], v182 offset:18976
	ds_read_b128 v[12:15], v16 offset:64
	ds_read_b128 v[210:213], v182 offset:64
	ds_read_b128 v[214:217], v182 offset:19008
	s_waitcnt lgkmcnt(7)
	v_mfma_f32_32x32x16_bf16 v[162:177], v[194:197], v[4:7], 0
	ds_read_b128 v[186:189], v16 offset:96
	ds_read_b128 v[234:237], v182 offset:96
	ds_read_b128 v[238:241], v182 offset:19040
	ds_read_b128 v[190:193], v16 offset:128
	ds_read_b128 v[242:245], v182 offset:128
	s_waitcnt lgkmcnt(11)
	v_mfma_f32_32x32x16_bf16 v[146:161], v[198:201], v[4:7], 0
	ds_read_b128 v[246:249], v182 offset:19072
	s_waitcnt lgkmcnt(10)
	v_mfma_f32_32x32x16_bf16 v[162:177], v[202:205], v[8:11], v[162:177]
	ds_read_b128 v[4:7], v16 offset:160
	ds_read_b128 v[194:197], v182 offset:160
	s_waitcnt lgkmcnt(11)
	v_mfma_f32_32x32x16_bf16 v[146:161], v[206:209], v[8:11], v[146:161]
	ds_read_b128 v[198:201], v182 offset:19104
	s_waitcnt lgkmcnt(10)
	v_mfma_f32_32x32x16_bf16 v[162:177], v[210:213], v[12:15], v[162:177]
	ds_read_b128 v[8:11], v16 offset:192
	ds_read_b128 v[202:205], v182 offset:192
	s_waitcnt lgkmcnt(11)
	v_mfma_f32_32x32x16_bf16 v[146:161], v[214:217], v[12:15], v[146:161]
	ds_read_b128 v[206:209], v182 offset:19136
	s_waitcnt lgkmcnt(10)
	v_mfma_f32_32x32x16_bf16 v[162:177], v[234:237], v[186:189], v[162:177]
	ds_read_b128 v[12:15], v16 offset:224
	ds_read_b128 v[210:213], v182 offset:224
	s_waitcnt lgkmcnt(11)
	v_mfma_f32_32x32x16_bf16 v[146:161], v[238:241], v[186:189], v[146:161]
	ds_read_b128 v[214:217], v182 offset:19168
	s_waitcnt lgkmcnt(10)
	v_mfma_f32_32x32x16_bf16 v[162:177], v[242:245], v[190:193], v[162:177]
	ds_read_b128 v[186:189], v16 offset:256
	ds_read_b128 v[234:237], v182 offset:256
	s_waitcnt lgkmcnt(11)
	v_mfma_f32_32x32x16_bf16 v[146:161], v[246:249], v[190:193], v[146:161]
	ds_read_b128 v[238:241], v182 offset:19200
	s_waitcnt lgkmcnt(10)
	v_mfma_f32_32x32x16_bf16 v[162:177], v[194:197], v[4:7], v[162:177]
	ds_read_b128 v[190:193], v16 offset:288
	ds_read_b128 v[242:245], v182 offset:288
	s_waitcnt lgkmcnt(11)
	v_mfma_f32_32x32x16_bf16 v[146:161], v[198:201], v[4:7], v[146:161]
	ds_read_b128 v[246:249], v182 offset:19232
	s_waitcnt lgkmcnt(10)
	v_mfma_f32_32x32x16_bf16 v[162:177], v[202:205], v[8:11], v[162:177]
	ds_read_b128 v[4:7], v16 offset:320
	ds_read_b128 v[194:197], v182 offset:320
	s_waitcnt lgkmcnt(11)
	v_mfma_f32_32x32x16_bf16 v[146:161], v[206:209], v[8:11], v[146:161]
	ds_read_b128 v[198:201], v182 offset:19264
	s_waitcnt lgkmcnt(10)
	v_mfma_f32_32x32x16_bf16 v[162:177], v[210:213], v[12:15], v[162:177]
	ds_read_b128 v[8:11], v16 offset:352
	ds_read_b128 v[202:205], v182 offset:352
	s_waitcnt lgkmcnt(11)
	v_mfma_f32_32x32x16_bf16 v[146:161], v[214:217], v[12:15], v[146:161]
	ds_read_b128 v[206:209], v182 offset:19296
	s_waitcnt lgkmcnt(10)
	v_mfma_f32_32x32x16_bf16 v[162:177], v[234:237], v[186:189], v[162:177]
	ds_read_b128 v[12:15], v16 offset:384
	ds_read_b128 v[210:213], v182 offset:384
	s_waitcnt lgkmcnt(11)
	v_mfma_f32_32x32x16_bf16 v[146:161], v[238:241], v[186:189], v[146:161]
	ds_read_b128 v[214:217], v182 offset:19328
	s_waitcnt lgkmcnt(10)
	v_mfma_f32_32x32x16_bf16 v[162:177], v[242:245], v[190:193], v[162:177]
	ds_read_b128 v[186:189], v16 offset:416
	ds_read_b128 v[234:237], v182 offset:416
	s_waitcnt lgkmcnt(11)
	v_mfma_f32_32x32x16_bf16 v[146:161], v[246:249], v[190:193], v[146:161]
	ds_read_b128 v[238:241], v182 offset:19360
	s_waitcnt lgkmcnt(10)
	v_mfma_f32_32x32x16_bf16 v[162:177], v[194:197], v[4:7], v[162:177]
	ds_read_b128 v[190:193], v16 offset:448
	ds_read_b128 v[242:245], v182 offset:448
	s_waitcnt lgkmcnt(11)
	v_mfma_f32_32x32x16_bf16 v[146:161], v[198:201], v[4:7], v[146:161]
	ds_read_b128 v[246:249], v182 offset:19392
	s_waitcnt lgkmcnt(10)
	v_mfma_f32_32x32x16_bf16 v[162:177], v[202:205], v[8:11], v[162:177]
	ds_read_b128 v[4:7], v16 offset:480
	ds_read_b128 v[194:197], v182 offset:480
	s_waitcnt lgkmcnt(11)
	v_mfma_f32_32x32x16_bf16 v[146:161], v[206:209], v[8:11], v[146:161]
	ds_read_b128 v[198:201], v182 offset:19424
	s_waitcnt lgkmcnt(10)
	v_mfma_f32_32x32x16_bf16 v[162:177], v[210:213], v[12:15], v[162:177]
	ds_read_b128 v[8:11], v16 offset:512
	ds_read_b128 v[202:205], v182 offset:512
	s_waitcnt lgkmcnt(11)
	v_mfma_f32_32x32x16_bf16 v[146:161], v[214:217], v[12:15], v[146:161]
	ds_read_b128 v[206:209], v182 offset:19456
	s_waitcnt lgkmcnt(10)
	v_mfma_f32_32x32x16_bf16 v[162:177], v[234:237], v[186:189], v[162:177]
	ds_read_b128 v[12:15], v16 offset:544
	ds_read_b128 v[210:213], v182 offset:544
	s_waitcnt lgkmcnt(11)
	v_mfma_f32_32x32x16_bf16 v[146:161], v[238:241], v[186:189], v[146:161]
	ds_read_b128 v[214:217], v182 offset:19488
	s_waitcnt lgkmcnt(10)
	v_mfma_f32_32x32x16_bf16 v[162:177], v[242:245], v[190:193], v[162:177]
	s_waitcnt lgkmcnt(9)
	v_mfma_f32_32x32x16_bf16 v[146:161], v[246:249], v[190:193], v[146:161]
	s_waitcnt lgkmcnt(7)
	v_mfma_f32_32x32x16_bf16 v[162:177], v[194:197], v[4:7], v[162:177]
	s_waitcnt lgkmcnt(6)
	v_mfma_f32_32x32x16_bf16 v[146:161], v[198:201], v[4:7], v[146:161]
	s_waitcnt lgkmcnt(4)
	v_mfma_f32_32x32x16_bf16 v[162:177], v[202:205], v[8:11], v[162:177]
	s_waitcnt lgkmcnt(3)
	v_mfma_f32_32x32x16_bf16 v[146:161], v[206:209], v[8:11], v[146:161]
	s_waitcnt lgkmcnt(1)
	v_mfma_f32_32x32x16_bf16 v[162:177], v[210:213], v[12:15], v[162:177]
	s_waitcnt lgkmcnt(0)
	v_mfma_f32_32x32x16_bf16 v[146:161], v[214:217], v[12:15], v[146:161]
	ds_read_b64_tr_b16 v[190:191], v184 offset:0
	ds_read_b64_tr_b16 v[192:193], v184 offset:4736
	ds_read_b64_tr_b16 v[194:195], v184 offset:64
	ds_read_b64_tr_b16 v[196:197], v184 offset:4800
	ds_read_b64_tr_b16 v[198:199], v184 offset:128
	ds_read_b64_tr_b16 v[200:201], v184 offset:4864
	ds_read_b64_tr_b16 v[202:203], v184 offset:192
	ds_read_b64_tr_b16 v[204:205], v184 offset:4928
	ds_read_b64_tr_b16 v[206:207], v184 offset:256
	ds_read_b64_tr_b16 v[208:209], v184 offset:4992
	ds_read_b64_tr_b16 v[210:211], v184 offset:320
	ds_read_b64_tr_b16 v[212:213], v184 offset:5056
	ds_read_b64_tr_b16 v[214:215], v184 offset:384
	ds_read_b64_tr_b16 v[216:217], v184 offset:5120
	v_max3_f32 v2, v162, v146, v163
	v_max3_f32 v17, v147, v164, v148
	v_max3_f32 v2, v2, v165, v149
	v_max3_f32 v17, v17, v166, v150
	v_max3_f32 v2, v2, v167, v151
	v_max3_f32 v17, v17, v168, v152
	v_max3_f32 v2, v2, v169, v153
	v_max3_f32 v17, v17, v170, v154
	v_max3_f32 v2, v2, v171, v155
	v_max3_f32 v17, v17, v172, v156
	v_max3_f32 v2, v2, v173, v157
	v_max3_f32 v17, v17, v174, v158
	v_max3_f32 v2, v2, v175, v159
	v_max3_f32 v17, v17, v176, v160
	v_max3_f32 v2, v2, v17, v177
	v_max_f32_e32 v2, v2, v161
	v_mov_b32_e32 v218, v2
	v_add_f32_e32 v233, 0x41000000, v178
	v_mov_b32_e32 v254, 0
	v_permlane32_swap_b32_e32 v2, v218
	v_max_f32_e32 v2, v2, v218
	v_mul_f32_e32 v2, 0x3e16c740, v2
	v_cmp_gt_f32_e32 vcc, v2, v233
	s_cbranch_vccz .Ldc2_nr0
	v_max_f32_e32 v2, v178, v2
	v_sub_f32_e32 v219, v178, v2
	v_exp_f32_e32 v219, v219
	v_mov_b32_e32 v178, v2
	v_mov_b32_e32 v218, v2
	v_mul_f32_e32 v183, v183, v219
	v_mul_f32_e32 v130, v130, v219
	v_mul_f32_e32 v131, v131, v219
	v_mul_f32_e32 v132, v132, v219
	v_mul_f32_e32 v133, v133, v219
	v_mul_f32_e32 v134, v134, v219
	v_mul_f32_e32 v135, v135, v219
	v_mul_f32_e32 v136, v136, v219
	v_mul_f32_e32 v137, v137, v219
	v_mul_f32_e32 v138, v138, v219
	v_mul_f32_e32 v139, v139, v219
	v_mul_f32_e32 v140, v140, v219
	v_mul_f32_e32 v141, v141, v219
	v_mul_f32_e32 v142, v142, v219
	v_mul_f32_e32 v143, v143, v219
	v_mul_f32_e32 v144, v144, v219
	v_mul_f32_e32 v145, v145, v219
	v_mul_f32_e32 v114, v114, v219
	v_mul_f32_e32 v115, v115, v219
	v_mul_f32_e32 v116, v116, v219
	v_mul_f32_e32 v117, v117, v219
	v_mul_f32_e32 v118, v118, v219
	v_mul_f32_e32 v119, v119, v219
	v_mul_f32_e32 v120, v120, v219
	v_mul_f32_e32 v121, v121, v219
	v_mul_f32_e32 v122, v122, v219
	v_mul_f32_e32 v123, v123, v219
	v_mul_f32_e32 v124, v124, v219
	v_mul_f32_e32 v125, v125, v219
	v_mul_f32_e32 v126, v126, v219
	v_mul_f32_e32 v127, v127, v219
	v_mul_f32_e32 v128, v128, v219
	v_mul_f32_e32 v129, v129, v219
	v_mul_f32_e32 v98, v98, v219
	v_mul_f32_e32 v99, v99, v219
	v_mul_f32_e32 v100, v100, v219
	v_mul_f32_e32 v101, v101, v219
	v_mul_f32_e32 v102, v102, v219
	v_mul_f32_e32 v103, v103, v219
	v_mul_f32_e32 v104, v104, v219
	v_mul_f32_e32 v105, v105, v219
	v_mul_f32_e32 v106, v106, v219
	v_mul_f32_e32 v107, v107, v219
	v_mul_f32_e32 v108, v108, v219
	v_mul_f32_e32 v109, v109, v219
	v_mul_f32_e32 v110, v110, v219
	v_mul_f32_e32 v111, v111, v219
	v_mul_f32_e32 v112, v112, v219
	v_mul_f32_e32 v113, v113, v219
	v_mul_f32_e32 v82, v82, v219
	v_mul_f32_e32 v83, v83, v219
	v_mul_f32_e32 v84, v84, v219
	v_mul_f32_e32 v85, v85, v219
	v_mul_f32_e32 v86, v86, v219
	v_mul_f32_e32 v87, v87, v219
	v_mul_f32_e32 v88, v88, v219
	v_mul_f32_e32 v89, v89, v219
	v_mul_f32_e32 v90, v90, v219
	v_mul_f32_e32 v91, v91, v219
	v_mul_f32_e32 v92, v92, v219
	v_mul_f32_e32 v93, v93, v219
	v_mul_f32_e32 v94, v94, v219
	v_mul_f32_e32 v95, v95, v219
	v_mul_f32_e32 v96, v96, v219
	v_mul_f32_e32 v97, v97, v219
	v_mul_f32_e32 v66, v66, v219
	v_mul_f32_e32 v67, v67, v219
	v_mul_f32_e32 v68, v68, v219
	v_mul_f32_e32 v69, v69, v219
	v_mul_f32_e32 v70, v70, v219
	v_mul_f32_e32 v71, v71, v219
	v_mul_f32_e32 v72, v72, v219
	v_mul_f32_e32 v73, v73, v219
	v_mul_f32_e32 v74, v74, v219
	v_mul_f32_e32 v75, v75, v219
	v_mul_f32_e32 v76, v76, v219
	v_mul_f32_e32 v77, v77, v219
	v_mul_f32_e32 v78, v78, v219
	v_mul_f32_e32 v79, v79, v219
	v_mul_f32_e32 v80, v80, v219
	v_mul_f32_e32 v81, v81, v219
	v_mul_f32_e32 v50, v50, v219
	v_mul_f32_e32 v51, v51, v219
	v_mul_f32_e32 v52, v52, v219
	v_mul_f32_e32 v53, v53, v219
	v_mul_f32_e32 v54, v54, v219
	v_mul_f32_e32 v55, v55, v219
	v_mul_f32_e32 v56, v56, v219
	v_mul_f32_e32 v57, v57, v219
	v_mul_f32_e32 v58, v58, v219
	v_mul_f32_e32 v59, v59, v219
	v_mul_f32_e32 v60, v60, v219
	v_mul_f32_e32 v61, v61, v219
	v_mul_f32_e32 v62, v62, v219
	v_mul_f32_e32 v63, v63, v219
	v_mul_f32_e32 v64, v64, v219
	v_mul_f32_e32 v65, v65, v219
	v_mul_f32_e32 v34, v34, v219
	v_mul_f32_e32 v35, v35, v219
	v_mul_f32_e32 v36, v36, v219
	v_mul_f32_e32 v37, v37, v219
	v_mul_f32_e32 v38, v38, v219
	v_mul_f32_e32 v39, v39, v219
	v_mul_f32_e32 v40, v40, v219
	v_mul_f32_e32 v41, v41, v219
	v_mul_f32_e32 v42, v42, v219
	v_mul_f32_e32 v43, v43, v219
	v_mul_f32_e32 v44, v44, v219
	v_mul_f32_e32 v45, v45, v219
	v_mul_f32_e32 v46, v46, v219
	v_mul_f32_e32 v47, v47, v219
	v_mul_f32_e32 v48, v48, v219
	v_mul_f32_e32 v49, v49, v219
	v_mul_f32_e32 v18, v18, v219
	v_mul_f32_e32 v19, v19, v219
	v_mul_f32_e32 v20, v20, v219
	v_mul_f32_e32 v21, v21, v219
	v_mul_f32_e32 v22, v22, v219
	v_mul_f32_e32 v23, v23, v219
	v_mul_f32_e32 v24, v24, v219
	v_mul_f32_e32 v25, v25, v219
	v_mul_f32_e32 v26, v26, v219
	v_mul_f32_e32 v27, v27, v219
	v_mul_f32_e32 v28, v28, v219
	v_mul_f32_e32 v29, v29, v219
	v_mul_f32_e32 v30, v30, v219
	v_mul_f32_e32 v31, v31, v219
	v_mul_f32_e32 v32, v32, v219
	v_mul_f32_e32 v33, v33, v219
.Ldc2_nr0:
	v_fma_f32 v162, v162, s42, -v178
	v_fma_f32 v146, v146, s42, -v178
	v_fma_f32 v163, v163, s42, -v178
	v_exp_f32_e32 v162, v162
	v_fma_f32 v147, v147, s42, -v178
	v_exp_f32_e32 v146, v146
	v_fma_f32 v164, v164, s42, -v178
	v_exp_f32_e32 v163, v163
	v_fma_f32 v148, v148, s42, -v178
	v_exp_f32_e32 v147, v147
	v_fma_f32 v165, v165, s42, -v178
	v_add_f32_e32 v218, v162, v146
	v_exp_f32_e32 v164, v164
	v_fma_f32 v149, v149, s42, -v178
	v_exp_f32_e32 v148, v148
	v_cvt_pk_bf16_f32 v4, v162, v163
	v_fma_f32 v166, v166, s42, -v178
	v_add_f32_e32 v233, v163, v147
	v_exp_f32_e32 v165, v165
	v_add_f32_e32 v254, v254, v218
	v_cvt_pk_bf16_f32 v12, v146, v147
	v_fma_f32 v150, v150, s42, -v178
	v_exp_f32_e32 v149, v149
	v_fma_f32 v167, v167, s42, -v178
	v_add_f32_e32 v17, v164, v148
	v_exp_f32_e32 v166, v166
	v_add_f32_e32 v254, v254, v233
	v_fma_f32 v151, v151, s42, -v178
	v_exp_f32_e32 v150, v150
	v_cvt_pk_bf16_f32 v5, v164, v165
	v_fma_f32 v168, v168, s42, -v178
	v_add_f32_e32 v219, v165, v149
	v_exp_f32_e32 v167, v167
	v_add_f32_e32 v254, v254, v17
	v_cvt_pk_bf16_f32 v13, v148, v149
	v_fma_f32 v152, v152, s42, -v178
	v_exp_f32_e32 v151, v151
	v_fma_f32 v169, v169, s42, -v178
	v_add_f32_e32 v218, v166, v150
	v_exp_f32_e32 v168, v168
	v_add_f32_e32 v254, v254, v219
	v_fma_f32 v153, v153, s42, -v178
	v_exp_f32_e32 v152, v152
	v_cvt_pk_bf16_f32 v6, v166, v167
	v_fma_f32 v170, v170, s42, -v178
	v_add_f32_e32 v233, v167, v151
	v_exp_f32_e32 v169, v169
	v_add_f32_e32 v254, v254, v218
	v_cvt_pk_bf16_f32 v14, v150, v151
	v_fma_f32 v154, v154, s42, -v178
	v_exp_f32_e32 v153, v153
	v_fma_f32 v171, v171, s42, -v178
	v_add_f32_e32 v17, v168, v152
	v_exp_f32_e32 v170, v170
	v_add_f32_e32 v254, v254, v233
	v_fma_f32 v155, v155, s42, -v178
	v_exp_f32_e32 v154, v154
	v_cvt_pk_bf16_f32 v7, v168, v169
	v_fma_f32 v172, v172, s42, -v178
	v_add_f32_e32 v219, v169, v153
	v_exp_f32_e32 v171, v171
	v_add_f32_e32 v254, v254, v17
	v_cvt_pk_bf16_f32 v15, v152, v153
	v_fma_f32 v156, v156, s42, -v178
	v_exp_f32_e32 v155, v155
	v_fma_f32 v173, v173, s42, -v178
	v_add_f32_e32 v218, v170, v154
	v_exp_f32_e32 v172, v172
	v_add_f32_e32 v254, v254, v219
	v_fma_f32 v157, v157, s42, -v178
	v_exp_f32_e32 v156, v156
	v_cvt_pk_bf16_f32 v8, v170, v171
	v_fma_f32 v174, v174, s42, -v178
	v_add_f32_e32 v233, v171, v155
	v_exp_f32_e32 v173, v173
	v_add_f32_e32 v254, v254, v218
	v_cvt_pk_bf16_f32 v186, v154, v155
	v_fma_f32 v158, v158, s42, -v178
	v_exp_f32_e32 v157, v157
	v_fma_f32 v175, v175, s42, -v178
	v_add_f32_e32 v17, v172, v156
	v_exp_f32_e32 v174, v174
	v_add_f32_e32 v254, v254, v233
	v_fma_f32 v159, v159, s42, -v178
	v_exp_f32_e32 v158, v158
	v_cvt_pk_bf16_f32 v9, v172, v173
	v_fma_f32 v176, v176, s42, -v178
	v_add_f32_e32 v219, v173, v157
	v_exp_f32_e32 v175, v175
	v_add_f32_e32 v254, v254, v17
	v_cvt_pk_bf16_f32 v187, v156, v157
	v_fma_f32 v160, v160, s42, -v178
	v_exp_f32_e32 v159, v159
	v_fma_f32 v177, v177, s42, -v178
	v_add_f32_e32 v218, v174, v158
	v_exp_f32_e32 v176, v176
	v_add_f32_e32 v254, v254, v219
	v_fma_f32 v161, v161, s42, -v178
	v_exp_f32_e32 v160, v160
	v_cvt_pk_bf16_f32 v10, v174, v175
	v_add_f32_e32 v233, v175, v159
	v_exp_f32_e32 v177, v177
	v_add_f32_e32 v254, v254, v218
	v_cvt_pk_bf16_f32 v188, v158, v159
	v_exp_f32_e32 v161, v161
	v_add_f32_e32 v17, v176, v160
	v_add_f32_e32 v254, v254, v233
	v_cvt_pk_bf16_f32 v11, v176, v177
	v_add_f32_e32 v219, v177, v161
	v_add_f32_e32 v254, v254, v17
	v_cvt_pk_bf16_f32 v189, v160, v161
	v_add_f32_e32 v254, v254, v219
	v_add_f32_e32 v183, v183, v254
	s_waitcnt lgkmcnt(12)
	v_mfma_f32_32x32x16_bf16 v[130:145], v[190:193], v[4:7], v[130:145]
	ds_read_b64_tr_b16 v[234:235], v184 offset:448
	ds_read_b64_tr_b16 v[236:237], v184 offset:5184
	s_waitcnt lgkmcnt(12)
	v_mfma_f32_32x32x16_bf16 v[114:129], v[194:197], v[4:7], v[114:129]
	ds_read_b64_tr_b16 v[238:239], v184 offset:9472
	ds_read_b64_tr_b16 v[240:241], v184 offset:14208
	s_waitcnt lgkmcnt(12)
	v_mfma_f32_32x32x16_bf16 v[98:113], v[198:201], v[4:7], v[98:113]
	ds_read_b64_tr_b16 v[242:243], v184 offset:9536
	ds_read_b64_tr_b16 v[244:245], v184 offset:14272
	s_waitcnt lgkmcnt(12)
	v_mfma_f32_32x32x16_bf16 v[82:97], v[202:205], v[4:7], v[82:97]
	ds_read_b64_tr_b16 v[246:247], v184 offset:9600
	ds_read_b64_tr_b16 v[248:249], v184 offset:14336
	s_waitcnt lgkmcnt(12)
	v_mfma_f32_32x32x16_bf16 v[66:81], v[206:209], v[4:7], v[66:81]
	ds_read_b64_tr_b16 v[250:251], v184 offset:9664
	ds_read_b64_tr_b16 v[252:253], v184 offset:14400
	s_waitcnt lgkmcnt(12)
	v_mfma_f32_32x32x16_bf16 v[50:65], v[210:213], v[4:7], v[50:65]
	ds_read_b64_tr_b16 v[190:191], v184 offset:9728
	ds_read_b64_tr_b16 v[192:193], v184 offset:14464
	s_waitcnt lgkmcnt(12)
	v_mfma_f32_32x32x16_bf16 v[34:49], v[214:217], v[4:7], v[34:49]
	ds_read_b64_tr_b16 v[194:195], v184 offset:9792
	ds_read_b64_tr_b16 v[196:197], v184 offset:14528
	s_waitcnt lgkmcnt(12)
	v_mfma_f32_32x32x16_bf16 v[18:33], v[234:237], v[4:7], v[18:33]
	ds_read_b64_tr_b16 v[198:199], v184 offset:9856
	ds_read_b64_tr_b16 v[200:201], v184 offset:14592
	s_waitcnt lgkmcnt(12)
	v_mfma_f32_32x32x16_bf16 v[130:145], v[238:241], v[8:11], v[130:145]
	ds_read_b64_tr_b16 v[202:203], v184 offset:9920
	ds_read_b64_tr_b16 v[204:205], v184 offset:14656
	s_waitcnt lgkmcnt(12)
	v_mfma_f32_32x32x16_bf16 v[114:129], v[242:245], v[8:11], v[114:129]
	ds_read_b64_tr_b16 v[206:207], v184 offset:18944
	ds_read_b64_tr_b16 v[208:209], v184 offset:23680
	s_waitcnt lgkmcnt(12)
	v_mfma_f32_32x32x16_bf16 v[98:113], v[246:249], v[8:11], v[98:113]
	ds_read_b64_tr_b16 v[210:211], v184 offset:19008
	ds_read_b64_tr_b16 v[212:213], v184 offset:23744
	s_waitcnt lgkmcnt(12)
	v_mfma_f32_32x32x16_bf16 v[82:97], v[250:253], v[8:11], v[82:97]
	ds_read_b64_tr_b16 v[214:215], v184 offset:19072
	ds_read_b64_tr_b16 v[216:217], v184 offset:23808
	s_waitcnt lgkmcnt(12)
	v_mfma_f32_32x32x16_bf16 v[66:81], v[190:193], v[8:11], v[66:81]
	ds_read_b64_tr_b16 v[234:235], v184 offset:19136
	ds_read_b64_tr_b16 v[236:237], v184 offset:23872
	s_waitcnt lgkmcnt(12)
	v_mfma_f32_32x32x16_bf16 v[50:65], v[194:197], v[8:11], v[50:65]
	ds_read_b64_tr_b16 v[238:239], v184 offset:19200
	ds_read_b64_tr_b16 v[240:241], v184 offset:23936
	s_waitcnt lgkmcnt(12)
	v_mfma_f32_32x32x16_bf16 v[34:49], v[198:201], v[8:11], v[34:49]
	ds_read_b64_tr_b16 v[242:243], v184 offset:19264
	ds_read_b64_tr_b16 v[244:245], v184 offset:24000
	s_waitcnt lgkmcnt(12)
	v_mfma_f32_32x32x16_bf16 v[18:33], v[202:205], v[8:11], v[18:33]
	ds_read_b64_tr_b16 v[246:247], v184 offset:19328
	ds_read_b64_tr_b16 v[248:249], v184 offset:24064
	s_waitcnt lgkmcnt(12)
	v_mfma_f32_32x32x16_bf16 v[130:145], v[206:209], v[12:15], v[130:145]
	ds_read_b64_tr_b16 v[250:251], v184 offset:19392
	ds_read_b64_tr_b16 v[252:253], v184 offset:24128
	s_waitcnt lgkmcnt(12)
	v_mfma_f32_32x32x16_bf16 v[114:129], v[210:213], v[12:15], v[114:129]
	ds_read_b64_tr_b16 v[190:191], v184 offset:28416
	ds_read_b64_tr_b16 v[192:193], v184 offset:33152
	s_waitcnt lgkmcnt(12)
	v_mfma_f32_32x32x16_bf16 v[98:113], v[214:217], v[12:15], v[98:113]
	ds_read_b64_tr_b16 v[194:195], v184 offset:28480
	ds_read_b64_tr_b16 v[196:197], v184 offset:33216
	s_waitcnt lgkmcnt(12)
	v_mfma_f32_32x32x16_bf16 v[82:97], v[234:237], v[12:15], v[82:97]
	ds_read_b64_tr_b16 v[198:199], v184 offset:28544
	ds_read_b64_tr_b16 v[200:201], v184 offset:33280
	s_waitcnt lgkmcnt(12)
	v_mfma_f32_32x32x16_bf16 v[66:81], v[238:241], v[12:15], v[66:81]
	ds_read_b64_tr_b16 v[202:203], v184 offset:28608
	ds_read_b64_tr_b16 v[204:205], v184 offset:33344
	s_waitcnt lgkmcnt(12)
	v_mfma_f32_32x32x16_bf16 v[50:65], v[242:245], v[12:15], v[50:65]
	ds_read_b64_tr_b16 v[206:207], v184 offset:28672
	ds_read_b64_tr_b16 v[208:209], v184 offset:33408
	s_waitcnt lgkmcnt(12)
	v_mfma_f32_32x32x16_bf16 v[34:49], v[246:249], v[12:15], v[34:49]
	ds_read_b64_tr_b16 v[210:211], v184 offset:28736
	ds_read_b64_tr_b16 v[212:213], v184 offset:33472
	s_waitcnt lgkmcnt(12)
	v_mfma_f32_32x32x16_bf16 v[18:33], v[250:253], v[12:15], v[18:33]
	ds_read_b64_tr_b16 v[214:215], v184 offset:28800
	ds_read_b64_tr_b16 v[216:217], v184 offset:33536
	s_waitcnt lgkmcnt(12)
	v_mfma_f32_32x32x16_bf16 v[130:145], v[190:193], v[186:189], v[130:145]
	ds_read_b64_tr_b16 v[234:235], v184 offset:28864
	ds_read_b64_tr_b16 v[236:237], v184 offset:33600
	s_waitcnt lgkmcnt(12)
	v_mfma_f32_32x32x16_bf16 v[114:129], v[194:197], v[186:189], v[114:129]
	s_waitcnt lgkmcnt(10)
	v_mfma_f32_32x32x16_bf16 v[98:113], v[198:201], v[186:189], v[98:113]
	s_waitcnt lgkmcnt(8)
	v_mfma_f32_32x32x16_bf16 v[82:97], v[202:205], v[186:189], v[82:97]
	s_waitcnt lgkmcnt(6)
	v_mfma_f32_32x32x16_bf16 v[66:81], v[206:209], v[186:189], v[66:81]
	s_waitcnt lgkmcnt(4)
	v_mfma_f32_32x32x16_bf16 v[50:65], v[210:213], v[186:189], v[50:65]
	s_waitcnt lgkmcnt(2)
	v_mfma_f32_32x32x16_bf16 v[34:49], v[214:217], v[186:189], v[34:49]
	s_waitcnt lgkmcnt(0)
	v_mfma_f32_32x32x16_bf16 v[18:33], v[234:237], v[186:189], v[18:33]
	s_waitcnt lgkmcnt(0)
	s_barrier
	ds_read_b128 v[4:7], v16 offset:0
	ds_read_b128 v[194:197], v182 offset:37888
	ds_read_b128 v[198:201], v182 offset:56832
	ds_read_b128 v[8:11], v16 offset:32
	ds_read_b128 v[202:205], v182 offset:37920
	ds_read_b128 v[206:209], v182 offset:56864
	ds_read_b128 v[12:15], v16 offset:64
	ds_read_b128 v[210:213], v182 offset:37952
	ds_read_b128 v[214:217], v182 offset:56896
	s_waitcnt lgkmcnt(7)
	v_mfma_f32_32x32x16_bf16 v[162:177], v[194:197], v[4:7], 0
	ds_read_b128 v[186:189], v16 offset:96
	ds_read_b128 v[234:237], v182 offset:37984
	ds_read_b128 v[238:241], v182 offset:56928
	ds_read_b128 v[190:193], v16 offset:128
	ds_read_b128 v[242:245], v182 offset:38016
	s_waitcnt lgkmcnt(11)
	v_mfma_f32_32x32x16_bf16 v[146:161], v[198:201], v[4:7], 0
	ds_read_b128 v[246:249], v182 offset:56960
	s_waitcnt lgkmcnt(10)
	v_mfma_f32_32x32x16_bf16 v[162:177], v[202:205], v[8:11], v[162:177]
	ds_read_b128 v[4:7], v16 offset:160
	ds_read_b128 v[194:197], v182 offset:38048
	s_waitcnt lgkmcnt(11)
	v_mfma_f32_32x32x16_bf16 v[146:161], v[206:209], v[8:11], v[146:161]
	ds_read_b128 v[198:201], v182 offset:56992
	s_waitcnt lgkmcnt(10)
	v_mfma_f32_32x32x16_bf16 v[162:177], v[210:213], v[12:15], v[162:177]
	ds_read_b128 v[8:11], v16 offset:192
	ds_read_b128 v[202:205], v182 offset:38080
	s_waitcnt lgkmcnt(11)
	v_mfma_f32_32x32x16_bf16 v[146:161], v[214:217], v[12:15], v[146:161]
	ds_read_b128 v[206:209], v182 offset:57024
	s_waitcnt lgkmcnt(10)
	v_mfma_f32_32x32x16_bf16 v[162:177], v[234:237], v[186:189], v[162:177]
	ds_read_b128 v[12:15], v16 offset:224
	ds_read_b128 v[210:213], v182 offset:38112
	s_waitcnt lgkmcnt(11)
	v_mfma_f32_32x32x16_bf16 v[146:161], v[238:241], v[186:189], v[146:161]
	ds_read_b128 v[214:217], v182 offset:57056
	s_waitcnt lgkmcnt(10)
	v_mfma_f32_32x32x16_bf16 v[162:177], v[242:245], v[190:193], v[162:177]
	ds_read_b128 v[186:189], v16 offset:256
	ds_read_b128 v[234:237], v182 offset:38144
	s_waitcnt lgkmcnt(11)
	v_mfma_f32_32x32x16_bf16 v[146:161], v[246:249], v[190:193], v[146:161]
	ds_read_b128 v[238:241], v182 offset:57088
	s_waitcnt lgkmcnt(10)
	v_mfma_f32_32x32x16_bf16 v[162:177], v[194:197], v[4:7], v[162:177]
	ds_read_b128 v[190:193], v16 offset:288
	ds_read_b128 v[242:245], v182 offset:38176
	s_waitcnt lgkmcnt(11)
	v_mfma_f32_32x32x16_bf16 v[146:161], v[198:201], v[4:7], v[146:161]
	ds_read_b128 v[246:249], v182 offset:57120
	s_waitcnt lgkmcnt(10)
	v_mfma_f32_32x32x16_bf16 v[162:177], v[202:205], v[8:11], v[162:177]
	ds_read_b128 v[4:7], v16 offset:320
	ds_read_b128 v[194:197], v182 offset:38208
	s_waitcnt lgkmcnt(11)
	v_mfma_f32_32x32x16_bf16 v[146:161], v[206:209], v[8:11], v[146:161]
	ds_read_b128 v[198:201], v182 offset:57152
	s_waitcnt lgkmcnt(10)
	v_mfma_f32_32x32x16_bf16 v[162:177], v[210:213], v[12:15], v[162:177]
	ds_read_b128 v[8:11], v16 offset:352
	ds_read_b128 v[202:205], v182 offset:38240
	s_waitcnt lgkmcnt(11)
	v_mfma_f32_32x32x16_bf16 v[146:161], v[214:217], v[12:15], v[146:161]
	ds_read_b128 v[206:209], v182 offset:57184
	s_waitcnt lgkmcnt(10)
	v_mfma_f32_32x32x16_bf16 v[162:177], v[234:237], v[186:189], v[162:177]
	ds_read_b128 v[12:15], v16 offset:384
	ds_read_b128 v[210:213], v182 offset:38272
	s_waitcnt lgkmcnt(11)
	v_mfma_f32_32x32x16_bf16 v[146:161], v[238:241], v[186:189], v[146:161]
	ds_read_b128 v[214:217], v182 offset:57216
	s_waitcnt lgkmcnt(10)
	v_mfma_f32_32x32x16_bf16 v[162:177], v[242:245], v[190:193], v[162:177]
	ds_read_b128 v[186:189], v16 offset:416
	ds_read_b128 v[234:237], v182 offset:38304
	s_waitcnt lgkmcnt(11)
	v_mfma_f32_32x32x16_bf16 v[146:161], v[246:249], v[190:193], v[146:161]
	ds_read_b128 v[238:241], v182 offset:57248
	s_waitcnt lgkmcnt(10)
	v_mfma_f32_32x32x16_bf16 v[162:177], v[194:197], v[4:7], v[162:177]
	ds_read_b128 v[190:193], v16 offset:448
	ds_read_b128 v[242:245], v182 offset:38336
	s_waitcnt lgkmcnt(11)
	v_mfma_f32_32x32x16_bf16 v[146:161], v[198:201], v[4:7], v[146:161]
	ds_read_b128 v[246:249], v182 offset:57280
	s_waitcnt lgkmcnt(10)
	v_mfma_f32_32x32x16_bf16 v[162:177], v[202:205], v[8:11], v[162:177]
	ds_read_b128 v[4:7], v16 offset:480
	ds_read_b128 v[194:197], v182 offset:38368
	s_waitcnt lgkmcnt(11)
	v_mfma_f32_32x32x16_bf16 v[146:161], v[206:209], v[8:11], v[146:161]
	ds_read_b128 v[198:201], v182 offset:57312
	s_waitcnt lgkmcnt(10)
	v_mfma_f32_32x32x16_bf16 v[162:177], v[210:213], v[12:15], v[162:177]
	ds_read_b128 v[8:11], v16 offset:512
	ds_read_b128 v[202:205], v182 offset:38400
	s_waitcnt lgkmcnt(11)
	v_mfma_f32_32x32x16_bf16 v[146:161], v[214:217], v[12:15], v[146:161]
	ds_read_b128 v[206:209], v182 offset:57344
	s_waitcnt lgkmcnt(10)
	v_mfma_f32_32x32x16_bf16 v[162:177], v[234:237], v[186:189], v[162:177]
	ds_read_b128 v[12:15], v16 offset:544
	ds_read_b128 v[210:213], v182 offset:38432
	s_waitcnt lgkmcnt(11)
	v_mfma_f32_32x32x16_bf16 v[146:161], v[238:241], v[186:189], v[146:161]
	ds_read_b128 v[214:217], v182 offset:57376
	s_waitcnt lgkmcnt(10)
	v_mfma_f32_32x32x16_bf16 v[162:177], v[242:245], v[190:193], v[162:177]
	s_waitcnt lgkmcnt(9)
	v_mfma_f32_32x32x16_bf16 v[146:161], v[246:249], v[190:193], v[146:161]
	s_waitcnt lgkmcnt(7)
	v_mfma_f32_32x32x16_bf16 v[162:177], v[194:197], v[4:7], v[162:177]
	s_waitcnt lgkmcnt(6)
	v_mfma_f32_32x32x16_bf16 v[146:161], v[198:201], v[4:7], v[146:161]
	s_waitcnt lgkmcnt(4)
	v_mfma_f32_32x32x16_bf16 v[162:177], v[202:205], v[8:11], v[162:177]
	s_waitcnt lgkmcnt(3)
	v_mfma_f32_32x32x16_bf16 v[146:161], v[206:209], v[8:11], v[146:161]
	s_waitcnt lgkmcnt(1)
	v_mfma_f32_32x32x16_bf16 v[162:177], v[210:213], v[12:15], v[162:177]
	s_waitcnt lgkmcnt(0)
	v_mfma_f32_32x32x16_bf16 v[146:161], v[214:217], v[12:15], v[146:161]
	ds_read_b64_tr_b16 v[190:191], v185 offset:0
	ds_read_b64_tr_b16 v[192:193], v185 offset:4736
	ds_read_b64_tr_b16 v[194:195], v185 offset:64
	ds_read_b64_tr_b16 v[196:197], v185 offset:4800
	ds_read_b64_tr_b16 v[198:199], v185 offset:128
	ds_read_b64_tr_b16 v[200:201], v185 offset:4864
	ds_read_b64_tr_b16 v[202:203], v185 offset:192
	ds_read_b64_tr_b16 v[204:205], v185 offset:4928
	ds_read_b64_tr_b16 v[206:207], v185 offset:256
	ds_read_b64_tr_b16 v[208:209], v185 offset:4992
	ds_read_b64_tr_b16 v[210:211], v185 offset:320
	ds_read_b64_tr_b16 v[212:213], v185 offset:5056
	ds_read_b64_tr_b16 v[214:215], v185 offset:384
	ds_read_b64_tr_b16 v[216:217], v185 offset:5120
	v_max3_f32 v2, v162, v146, v163
	v_max3_f32 v17, v147, v164, v148
	v_max3_f32 v2, v2, v165, v149
	v_max3_f32 v17, v17, v166, v150
	v_max3_f32 v2, v2, v167, v151
	v_max3_f32 v17, v17, v168, v152
	v_max3_f32 v2, v2, v169, v153
	v_max3_f32 v17, v17, v170, v154
	v_max3_f32 v2, v2, v171, v155
	v_max3_f32 v17, v17, v172, v156
	v_max3_f32 v2, v2, v173, v157
	v_max3_f32 v17, v17, v174, v158
	v_max3_f32 v2, v2, v175, v159
	v_max3_f32 v17, v17, v176, v160
	v_max3_f32 v2, v2, v17, v177
	v_max_f32_e32 v2, v2, v161
	v_mov_b32_e32 v218, v2
	v_add_f32_e32 v233, 0x41000000, v178
	v_mov_b32_e32 v254, 0
	v_permlane32_swap_b32_e32 v2, v218
	v_max_f32_e32 v2, v2, v218
	v_mul_f32_e32 v2, 0x3e16c740, v2
	v_cmp_gt_f32_e32 vcc, v2, v233
	s_cbranch_vccz .Ldc2_nr1
	v_max_f32_e32 v2, v178, v2
	v_sub_f32_e32 v219, v178, v2
	v_exp_f32_e32 v219, v219
	v_mov_b32_e32 v178, v2
	v_mov_b32_e32 v218, v2
	v_mul_f32_e32 v183, v183, v219
	v_mul_f32_e32 v130, v130, v219
	v_mul_f32_e32 v131, v131, v219
	v_mul_f32_e32 v132, v132, v219
	v_mul_f32_e32 v133, v133, v219
	v_mul_f32_e32 v134, v134, v219
	v_mul_f32_e32 v135, v135, v219
	v_mul_f32_e32 v136, v136, v219
	v_mul_f32_e32 v137, v137, v219
	v_mul_f32_e32 v138, v138, v219
	v_mul_f32_e32 v139, v139, v219
	v_mul_f32_e32 v140, v140, v219
	v_mul_f32_e32 v141, v141, v219
	v_mul_f32_e32 v142, v142, v219
	v_mul_f32_e32 v143, v143, v219
	v_mul_f32_e32 v144, v144, v219
	v_mul_f32_e32 v145, v145, v219
	v_mul_f32_e32 v114, v114, v219
	v_mul_f32_e32 v115, v115, v219
	v_mul_f32_e32 v116, v116, v219
	v_mul_f32_e32 v117, v117, v219
	v_mul_f32_e32 v118, v118, v219
	v_mul_f32_e32 v119, v119, v219
	v_mul_f32_e32 v120, v120, v219
	v_mul_f32_e32 v121, v121, v219
	v_mul_f32_e32 v122, v122, v219
	v_mul_f32_e32 v123, v123, v219
	v_mul_f32_e32 v124, v124, v219
	v_mul_f32_e32 v125, v125, v219
	v_mul_f32_e32 v126, v126, v219
	v_mul_f32_e32 v127, v127, v219
	v_mul_f32_e32 v128, v128, v219
	v_mul_f32_e32 v129, v129, v219
	v_mul_f32_e32 v98, v98, v219
	v_mul_f32_e32 v99, v99, v219
	v_mul_f32_e32 v100, v100, v219
	v_mul_f32_e32 v101, v101, v219
	v_mul_f32_e32 v102, v102, v219
	v_mul_f32_e32 v103, v103, v219
	v_mul_f32_e32 v104, v104, v219
	v_mul_f32_e32 v105, v105, v219
	v_mul_f32_e32 v106, v106, v219
	v_mul_f32_e32 v107, v107, v219
	v_mul_f32_e32 v108, v108, v219
	v_mul_f32_e32 v109, v109, v219
	v_mul_f32_e32 v110, v110, v219
	v_mul_f32_e32 v111, v111, v219
	v_mul_f32_e32 v112, v112, v219
	v_mul_f32_e32 v113, v113, v219
	v_mul_f32_e32 v82, v82, v219
	v_mul_f32_e32 v83, v83, v219
	v_mul_f32_e32 v84, v84, v219
	v_mul_f32_e32 v85, v85, v219
	v_mul_f32_e32 v86, v86, v219
	v_mul_f32_e32 v87, v87, v219
	v_mul_f32_e32 v88, v88, v219
	v_mul_f32_e32 v89, v89, v219
	v_mul_f32_e32 v90, v90, v219
	v_mul_f32_e32 v91, v91, v219
	v_mul_f32_e32 v92, v92, v219
	v_mul_f32_e32 v93, v93, v219
	v_mul_f32_e32 v94, v94, v219
	v_mul_f32_e32 v95, v95, v219
	v_mul_f32_e32 v96, v96, v219
	v_mul_f32_e32 v97, v97, v219
	v_mul_f32_e32 v66, v66, v219
	v_mul_f32_e32 v67, v67, v219
	v_mul_f32_e32 v68, v68, v219
	v_mul_f32_e32 v69, v69, v219
	v_mul_f32_e32 v70, v70, v219
	v_mul_f32_e32 v71, v71, v219
	v_mul_f32_e32 v72, v72, v219
	v_mul_f32_e32 v73, v73, v219
	v_mul_f32_e32 v74, v74, v219
	v_mul_f32_e32 v75, v75, v219
	v_mul_f32_e32 v76, v76, v219
	v_mul_f32_e32 v77, v77, v219
	v_mul_f32_e32 v78, v78, v219
	v_mul_f32_e32 v79, v79, v219
	v_mul_f32_e32 v80, v80, v219
	v_mul_f32_e32 v81, v81, v219
	v_mul_f32_e32 v50, v50, v219
	v_mul_f32_e32 v51, v51, v219
	v_mul_f32_e32 v52, v52, v219
	v_mul_f32_e32 v53, v53, v219
	v_mul_f32_e32 v54, v54, v219
	v_mul_f32_e32 v55, v55, v219
	v_mul_f32_e32 v56, v56, v219
	v_mul_f32_e32 v57, v57, v219
	v_mul_f32_e32 v58, v58, v219
	v_mul_f32_e32 v59, v59, v219
	v_mul_f32_e32 v60, v60, v219
	v_mul_f32_e32 v61, v61, v219
	v_mul_f32_e32 v62, v62, v219
	v_mul_f32_e32 v63, v63, v219
	v_mul_f32_e32 v64, v64, v219
	v_mul_f32_e32 v65, v65, v219
	v_mul_f32_e32 v34, v34, v219
	v_mul_f32_e32 v35, v35, v219
	v_mul_f32_e32 v36, v36, v219
	v_mul_f32_e32 v37, v37, v219
	v_mul_f32_e32 v38, v38, v219
	v_mul_f32_e32 v39, v39, v219
	v_mul_f32_e32 v40, v40, v219
	v_mul_f32_e32 v41, v41, v219
	v_mul_f32_e32 v42, v42, v219
	v_mul_f32_e32 v43, v43, v219
	v_mul_f32_e32 v44, v44, v219
	v_mul_f32_e32 v45, v45, v219
	v_mul_f32_e32 v46, v46, v219
	v_mul_f32_e32 v47, v47, v219
	v_mul_f32_e32 v48, v48, v219
	v_mul_f32_e32 v49, v49, v219
	v_mul_f32_e32 v18, v18, v219
	v_mul_f32_e32 v19, v19, v219
	v_mul_f32_e32 v20, v20, v219
	v_mul_f32_e32 v21, v21, v219
	v_mul_f32_e32 v22, v22, v219
	v_mul_f32_e32 v23, v23, v219
	v_mul_f32_e32 v24, v24, v219
	v_mul_f32_e32 v25, v25, v219
	v_mul_f32_e32 v26, v26, v219
	v_mul_f32_e32 v27, v27, v219
	v_mul_f32_e32 v28, v28, v219
	v_mul_f32_e32 v29, v29, v219
	v_mul_f32_e32 v30, v30, v219
	v_mul_f32_e32 v31, v31, v219
	v_mul_f32_e32 v32, v32, v219
	v_mul_f32_e32 v33, v33, v219
.Ldc2_nr1:
	v_fma_f32 v162, v162, s42, -v178
	v_fma_f32 v146, v146, s42, -v178
	v_fma_f32 v163, v163, s42, -v178
	v_exp_f32_e32 v162, v162
	v_fma_f32 v147, v147, s42, -v178
	v_exp_f32_e32 v146, v146
	v_fma_f32 v164, v164, s42, -v178
	v_exp_f32_e32 v163, v163
	v_fma_f32 v148, v148, s42, -v178
	v_exp_f32_e32 v147, v147
	v_fma_f32 v165, v165, s42, -v178
	v_add_f32_e32 v218, v162, v146
	v_exp_f32_e32 v164, v164
	v_fma_f32 v149, v149, s42, -v178
	v_exp_f32_e32 v148, v148
	v_cvt_pk_bf16_f32 v4, v162, v163
	v_fma_f32 v166, v166, s42, -v178
	v_add_f32_e32 v233, v163, v147
	v_exp_f32_e32 v165, v165
	v_add_f32_e32 v254, v254, v218
	v_cvt_pk_bf16_f32 v12, v146, v147
	v_fma_f32 v150, v150, s42, -v178
	v_exp_f32_e32 v149, v149
	v_fma_f32 v167, v167, s42, -v178
	v_add_f32_e32 v17, v164, v148
	v_exp_f32_e32 v166, v166
	v_add_f32_e32 v254, v254, v233
	v_fma_f32 v151, v151, s42, -v178
	v_exp_f32_e32 v150, v150
	v_cvt_pk_bf16_f32 v5, v164, v165
	v_fma_f32 v168, v168, s42, -v178
	v_add_f32_e32 v219, v165, v149
	v_exp_f32_e32 v167, v167
	v_add_f32_e32 v254, v254, v17
	v_cvt_pk_bf16_f32 v13, v148, v149
	v_fma_f32 v152, v152, s42, -v178
	v_exp_f32_e32 v151, v151
	v_fma_f32 v169, v169, s42, -v178
	v_add_f32_e32 v218, v166, v150
	v_exp_f32_e32 v168, v168
	v_add_f32_e32 v254, v254, v219
	v_fma_f32 v153, v153, s42, -v178
	v_exp_f32_e32 v152, v152
	v_cvt_pk_bf16_f32 v6, v166, v167
	v_fma_f32 v170, v170, s42, -v178
	v_add_f32_e32 v233, v167, v151
	v_exp_f32_e32 v169, v169
	v_add_f32_e32 v254, v254, v218
	v_cvt_pk_bf16_f32 v14, v150, v151
	v_fma_f32 v154, v154, s42, -v178
	v_exp_f32_e32 v153, v153
	v_fma_f32 v171, v171, s42, -v178
	v_add_f32_e32 v17, v168, v152
	v_exp_f32_e32 v170, v170
	v_add_f32_e32 v254, v254, v233
	v_fma_f32 v155, v155, s42, -v178
	v_exp_f32_e32 v154, v154
	v_cvt_pk_bf16_f32 v7, v168, v169
	v_fma_f32 v172, v172, s42, -v178
	v_add_f32_e32 v219, v169, v153
	v_exp_f32_e32 v171, v171
	v_add_f32_e32 v254, v254, v17
	v_cvt_pk_bf16_f32 v15, v152, v153
	v_fma_f32 v156, v156, s42, -v178
	v_exp_f32_e32 v155, v155
	v_fma_f32 v173, v173, s42, -v178
	v_add_f32_e32 v218, v170, v154
	v_exp_f32_e32 v172, v172
	v_add_f32_e32 v254, v254, v219
	v_fma_f32 v157, v157, s42, -v178
	v_exp_f32_e32 v156, v156
	v_cvt_pk_bf16_f32 v8, v170, v171
	v_fma_f32 v174, v174, s42, -v178
	v_add_f32_e32 v233, v171, v155
	v_exp_f32_e32 v173, v173
	v_add_f32_e32 v254, v254, v218
	v_cvt_pk_bf16_f32 v186, v154, v155
	v_fma_f32 v158, v158, s42, -v178
	v_exp_f32_e32 v157, v157
	v_fma_f32 v175, v175, s42, -v178
	v_add_f32_e32 v17, v172, v156
	v_exp_f32_e32 v174, v174
	v_add_f32_e32 v254, v254, v233
	v_fma_f32 v159, v159, s42, -v178
	v_exp_f32_e32 v158, v158
	v_cvt_pk_bf16_f32 v9, v172, v173
	v_fma_f32 v176, v176, s42, -v178
	v_add_f32_e32 v219, v173, v157
	v_exp_f32_e32 v175, v175
	v_add_f32_e32 v254, v254, v17
	v_cvt_pk_bf16_f32 v187, v156, v157
	v_fma_f32 v160, v160, s42, -v178
	v_exp_f32_e32 v159, v159
	v_fma_f32 v177, v177, s42, -v178
	v_add_f32_e32 v218, v174, v158
	v_exp_f32_e32 v176, v176
	v_add_f32_e32 v254, v254, v219
	v_fma_f32 v161, v161, s42, -v178
	v_exp_f32_e32 v160, v160
	v_cvt_pk_bf16_f32 v10, v174, v175
	v_add_f32_e32 v233, v175, v159
	v_exp_f32_e32 v177, v177
	v_add_f32_e32 v254, v254, v218
	v_cvt_pk_bf16_f32 v188, v158, v159
	v_exp_f32_e32 v161, v161
	v_add_f32_e32 v17, v176, v160
	v_add_f32_e32 v254, v254, v233
	v_cvt_pk_bf16_f32 v11, v176, v177
	v_add_f32_e32 v219, v177, v161
	v_add_f32_e32 v254, v254, v17
	v_cvt_pk_bf16_f32 v189, v160, v161
	v_add_f32_e32 v254, v254, v219
	v_add_f32_e32 v183, v183, v254
	s_waitcnt lgkmcnt(12)
	v_mfma_f32_32x32x16_bf16 v[130:145], v[190:193], v[4:7], v[130:145]
	ds_read_b64_tr_b16 v[234:235], v185 offset:448
	ds_read_b64_tr_b16 v[236:237], v185 offset:5184
	s_waitcnt lgkmcnt(12)
	v_mfma_f32_32x32x16_bf16 v[114:129], v[194:197], v[4:7], v[114:129]
	ds_read_b64_tr_b16 v[238:239], v185 offset:9472
	ds_read_b64_tr_b16 v[240:241], v185 offset:14208
	s_waitcnt lgkmcnt(12)
	v_mfma_f32_32x32x16_bf16 v[98:113], v[198:201], v[4:7], v[98:113]
	ds_read_b64_tr_b16 v[242:243], v185 offset:9536
	ds_read_b64_tr_b16 v[244:245], v185 offset:14272
	s_waitcnt lgkmcnt(12)
	v_mfma_f32_32x32x16_bf16 v[82:97], v[202:205], v[4:7], v[82:97]
	ds_read_b64_tr_b16 v[246:247], v185 offset:9600
	ds_read_b64_tr_b16 v[248:249], v185 offset:14336
	s_waitcnt lgkmcnt(12)
	v_mfma_f32_32x32x16_bf16 v[66:81], v[206:209], v[4:7], v[66:81]
	ds_read_b64_tr_b16 v[250:251], v185 offset:9664
	ds_read_b64_tr_b16 v[252:253], v185 offset:14400
	s_waitcnt lgkmcnt(12)
	v_mfma_f32_32x32x16_bf16 v[50:65], v[210:213], v[4:7], v[50:65]
	ds_read_b64_tr_b16 v[190:191], v185 offset:9728
	ds_read_b64_tr_b16 v[192:193], v185 offset:14464
	s_waitcnt lgkmcnt(12)
	v_mfma_f32_32x32x16_bf16 v[34:49], v[214:217], v[4:7], v[34:49]
	ds_read_b64_tr_b16 v[194:195], v185 offset:9792
	ds_read_b64_tr_b16 v[196:197], v185 offset:14528
	s_waitcnt lgkmcnt(12)
	v_mfma_f32_32x32x16_bf16 v[18:33], v[234:237], v[4:7], v[18:33]
	ds_read_b64_tr_b16 v[198:199], v185 offset:9856
	ds_read_b64_tr_b16 v[200:201], v185 offset:14592
	s_waitcnt lgkmcnt(12)
	v_mfma_f32_32x32x16_bf16 v[130:145], v[238:241], v[8:11], v[130:145]
	ds_read_b64_tr_b16 v[202:203], v185 offset:9920
	ds_read_b64_tr_b16 v[204:205], v185 offset:14656
	s_waitcnt lgkmcnt(12)
	v_mfma_f32_32x32x16_bf16 v[114:129], v[242:245], v[8:11], v[114:129]
	ds_read_b64_tr_b16 v[206:207], v185 offset:18944
	ds_read_b64_tr_b16 v[208:209], v185 offset:23680
	s_waitcnt lgkmcnt(12)
	v_mfma_f32_32x32x16_bf16 v[98:113], v[246:249], v[8:11], v[98:113]
	ds_read_b64_tr_b16 v[210:211], v185 offset:19008
	ds_read_b64_tr_b16 v[212:213], v185 offset:23744
	s_waitcnt lgkmcnt(12)
	v_mfma_f32_32x32x16_bf16 v[82:97], v[250:253], v[8:11], v[82:97]
	ds_read_b64_tr_b16 v[214:215], v185 offset:19072
	ds_read_b64_tr_b16 v[216:217], v185 offset:23808
	s_waitcnt lgkmcnt(12)
	v_mfma_f32_32x32x16_bf16 v[66:81], v[190:193], v[8:11], v[66:81]
	ds_read_b64_tr_b16 v[234:235], v185 offset:19136
	ds_read_b64_tr_b16 v[236:237], v185 offset:23872
	s_waitcnt lgkmcnt(12)
	v_mfma_f32_32x32x16_bf16 v[50:65], v[194:197], v[8:11], v[50:65]
	ds_read_b64_tr_b16 v[238:239], v185 offset:19200
	ds_read_b64_tr_b16 v[240:241], v185 offset:23936
	s_waitcnt lgkmcnt(12)
	v_mfma_f32_32x32x16_bf16 v[34:49], v[198:201], v[8:11], v[34:49]
	ds_read_b64_tr_b16 v[242:243], v185 offset:19264
	ds_read_b64_tr_b16 v[244:245], v185 offset:24000
	s_waitcnt lgkmcnt(12)
	v_mfma_f32_32x32x16_bf16 v[18:33], v[202:205], v[8:11], v[18:33]
	ds_read_b64_tr_b16 v[246:247], v185 offset:19328
	ds_read_b64_tr_b16 v[248:249], v185 offset:24064
	s_waitcnt lgkmcnt(12)
	v_mfma_f32_32x32x16_bf16 v[130:145], v[206:209], v[12:15], v[130:145]
	ds_read_b64_tr_b16 v[250:251], v185 offset:19392
	ds_read_b64_tr_b16 v[252:253], v185 offset:24128
	s_waitcnt lgkmcnt(12)
	v_mfma_f32_32x32x16_bf16 v[114:129], v[210:213], v[12:15], v[114:129]
	ds_read_b64_tr_b16 v[190:191], v185 offset:28416
	ds_read_b64_tr_b16 v[192:193], v185 offset:33152
	s_waitcnt lgkmcnt(12)
	v_mfma_f32_32x32x16_bf16 v[98:113], v[214:217], v[12:15], v[98:113]
	ds_read_b64_tr_b16 v[194:195], v185 offset:28480
	ds_read_b64_tr_b16 v[196:197], v185 offset:33216
	s_waitcnt lgkmcnt(12)
	v_mfma_f32_32x32x16_bf16 v[82:97], v[234:237], v[12:15], v[82:97]
	ds_read_b64_tr_b16 v[198:199], v185 offset:28544
	ds_read_b64_tr_b16 v[200:201], v185 offset:33280
	s_waitcnt lgkmcnt(12)
	v_mfma_f32_32x32x16_bf16 v[66:81], v[238:241], v[12:15], v[66:81]
	ds_read_b64_tr_b16 v[202:203], v185 offset:28608
	ds_read_b64_tr_b16 v[204:205], v185 offset:33344
	s_waitcnt lgkmcnt(12)
	v_mfma_f32_32x32x16_bf16 v[50:65], v[242:245], v[12:15], v[50:65]
	ds_read_b64_tr_b16 v[206:207], v185 offset:28672
	ds_read_b64_tr_b16 v[208:209], v185 offset:33408
	s_waitcnt lgkmcnt(12)
	v_mfma_f32_32x32x16_bf16 v[34:49], v[246:249], v[12:15], v[34:49]
	ds_read_b64_tr_b16 v[210:211], v185 offset:28736
	ds_read_b64_tr_b16 v[212:213], v185 offset:33472
	s_waitcnt lgkmcnt(12)
	v_mfma_f32_32x32x16_bf16 v[18:33], v[250:253], v[12:15], v[18:33]
	ds_read_b64_tr_b16 v[214:215], v185 offset:28800
	ds_read_b64_tr_b16 v[216:217], v185 offset:33536
	s_waitcnt lgkmcnt(12)
	v_mfma_f32_32x32x16_bf16 v[130:145], v[190:193], v[186:189], v[130:145]
	ds_read_b64_tr_b16 v[234:235], v185 offset:28864
	ds_read_b64_tr_b16 v[236:237], v185 offset:33600
	s_waitcnt lgkmcnt(12)
	v_mfma_f32_32x32x16_bf16 v[114:129], v[194:197], v[186:189], v[114:129]
	s_waitcnt lgkmcnt(10)
	v_mfma_f32_32x32x16_bf16 v[98:113], v[198:201], v[186:189], v[98:113]
	s_waitcnt lgkmcnt(8)
	v_mfma_f32_32x32x16_bf16 v[82:97], v[202:205], v[186:189], v[82:97]
	s_waitcnt lgkmcnt(6)
	v_mfma_f32_32x32x16_bf16 v[66:81], v[206:209], v[186:189], v[66:81]
	s_waitcnt lgkmcnt(4)
	v_mfma_f32_32x32x16_bf16 v[50:65], v[210:213], v[186:189], v[50:65]
	s_waitcnt lgkmcnt(2)
	v_mfma_f32_32x32x16_bf16 v[34:49], v[214:217], v[186:189], v[34:49]
	s_waitcnt lgkmcnt(0)
	v_mfma_f32_32x32x16_bf16 v[18:33], v[234:237], v[186:189], v[18:33]
	s_waitcnt lgkmcnt(0)
	s_barrier
	s_add_i32 s14, s14, 2
	s_cmp_gt_u32 s14, 61
	s_cbranch_scc0 .LBB0_911
	s_branch .LBB0_916
